# scan consumer: y transposes of the previous 16-step group interleaved as fillers in the DPP hazard gaps (double-buffered partials), replacing s_nop pads
# speedup vs baseline: 1.0366x; 1.0033x over previous
.Lscan_cons_chunk:
	v_cndmask_b32_e64 v2, v4, v5, s[42:43]
	v_add_lshl_u32 v2, v2, s80, 10
	v_mov_b32_e32 v3, v180
	s_add_i32 s28, s28, 0x10000
	v_lshl_add_u64 v[2:3], v[0:1], 0, v[2:3]
	v_add_u32_e32 v5, 64, v5
	v_subrev_u32_e32 v4, 64, v4
	s_waitcnt lgkmcnt(3)
	v_fma_mix_f32 v12, v6, v20, v180 op_sel_hi:[0,1,0]
	v_fma_mix_f32 v12, v7, v20, v12 op_sel:[0,1,0] op_sel_hi:[0,1,0]
	v_fma_mix_f32 v12, v8, v21, v12 op_sel_hi:[0,1,0]
	v_fma_mix_f32 v12, v9, v21, v12 op_sel:[0,1,0] op_sel_hi:[0,1,0]
	s_nop 1
	v_add_f32_dpp v12, v12, v12 row_ror:1 row_mask:0xf bank_mask:0xf bound_ctrl:1
	s_nop 1
	v_add_f32_dpp v12, v12, v12 row_ror:2 row_mask:0xf bank_mask:0xf bound_ctrl:1
	v_pk_fma_f32 v[48:49], v[28:29], v[66:67], v[6:7] op_sel_hi:[1,0,1]
	v_pk_fma_f32 v[50:51], v[30:31], v[66:67], v[8:9] op_sel_hi:[1,0,1]
	v_add_f32_dpp v12, v12, v12 row_ror:4 row_mask:0xf bank_mask:0xf bound_ctrl:1
	s_nop 1
	v_add_f32_dpp v12, v12, v12 row_ror:8 row_mask:0xf bank_mask:0xf bound_ctrl:1
	v_pk_fma_f32 v[6:7], v[24:25], v[12:13], v[48:49] op_sel_hi:[1,0,1] neg_lo:[1,0,0] neg_hi:[1,0,0]
	v_pk_fma_f32 v[8:9], v[26:27], v[12:13], v[50:51] op_sel_hi:[1,0,1] neg_lo:[1,0,0] neg_hi:[1,0,0]
	ds_read_b128 v[88:91], v10 offset:2304
	ds_read_b128 v[96:99], v10 offset:2816
	ds_read_b128 v[92:95], v10 offset:2560
	s_waitcnt lgkmcnt(3)
	v_fma_mix_f32 v12, v6, v36, v180 op_sel_hi:[0,1,0]
	v_fma_mix_f32 v12, v7, v36, v12 op_sel:[0,1,0] op_sel_hi:[0,1,0]
	v_fma_mix_f32 v12, v8, v37, v12 op_sel_hi:[0,1,0]
	v_fma_mix_f32 v12, v9, v37, v12 op_sel:[0,1,0] op_sel_hi:[0,1,0]
	v_fma_mix_f32 v52, v6, v22, v180 op_sel_hi:[0,1,0]
	v_fma_mix_f32 v52, v7, v22, v52 op_sel:[0,1,0] op_sel_hi:[0,1,0]
	v_add_f32_dpp v12, v12, v12 row_ror:1 row_mask:0xf bank_mask:0xf bound_ctrl:1
	v_fma_mix_f32 v52, v8, v23, v52 op_sel_hi:[0,1,0]
	v_fma_mix_f32 v52, v9, v23, v52 op_sel:[0,1,0] op_sel_hi:[0,1,0]
	v_add_f32_dpp v12, v12, v12 row_ror:2 row_mask:0xf bank_mask:0xf bound_ctrl:1
	v_pk_fma_f32 v[48:49], v[44:45], v[66:67], v[6:7] op_sel:[0,1,0]
	v_pk_fma_f32 v[50:51], v[46:47], v[66:67], v[8:9] op_sel:[0,1,0]
	v_add_f32_dpp v12, v12, v12 row_ror:4 row_mask:0xf bank_mask:0xf bound_ctrl:1
	s_nop 1
	v_add_f32_dpp v12, v12, v12 row_ror:8 row_mask:0xf bank_mask:0xf bound_ctrl:1
	v_pk_fma_f32 v[6:7], v[40:41], v[12:13], v[48:49] op_sel_hi:[1,0,1] neg_lo:[1,0,0] neg_hi:[1,0,0]
	v_pk_fma_f32 v[8:9], v[42:43], v[12:13], v[50:51] op_sel_hi:[1,0,1] neg_lo:[1,0,0] neg_hi:[1,0,0]
	ds_read_b128 v[110:113], v10 offset:3328
	ds_read_b128 v[106:109], v10 offset:3072
	ds_read_b128 v[118:121], v10 offset:3840
	ds_read_b128 v[114:117], v10 offset:3584
	ds_read_b128 v[70:73], v11 offset:256
	s_waitcnt lgkmcnt(5)
	v_fma_mix_f32 v12, v6, v88, v180 op_sel_hi:[0,1,0]
	v_fma_mix_f32 v12, v7, v88, v12 op_sel:[0,1,0] op_sel_hi:[0,1,0]
	v_fma_mix_f32 v12, v8, v89, v12 op_sel_hi:[0,1,0]
	v_fma_mix_f32 v12, v9, v89, v12 op_sel:[0,1,0] op_sel_hi:[0,1,0]
	v_fma_mix_f32 v53, v6, v38, v180 op_sel_hi:[0,1,0]
	v_fma_mix_f32 v53, v7, v38, v53 op_sel:[0,1,0] op_sel_hi:[0,1,0]
	v_add_f32_dpp v12, v12, v12 row_ror:1 row_mask:0xf bank_mask:0xf bound_ctrl:1
	v_fma_mix_f32 v53, v8, v39, v53 op_sel_hi:[0,1,0]
	v_fma_mix_f32 v53, v9, v39, v53 op_sel:[0,1,0] op_sel_hi:[0,1,0]
	v_add_f32_dpp v12, v12, v12 row_ror:2 row_mask:0xf bank_mask:0xf bound_ctrl:1
	v_pk_fma_f32 v[48:49], v[96:97], v[68:69], v[6:7] op_sel_hi:[1,0,1]
	v_pk_fma_f32 v[50:51], v[98:99], v[68:69], v[8:9] op_sel_hi:[1,0,1]
	v_add_f32_dpp v12, v12, v12 row_ror:4 row_mask:0xf bank_mask:0xf bound_ctrl:1
	s_nop 1
	v_add_f32_dpp v12, v12, v12 row_ror:8 row_mask:0xf bank_mask:0xf bound_ctrl:1
	v_pk_fma_f32 v[6:7], v[92:93], v[12:13], v[48:49] op_sel_hi:[1,0,1] neg_lo:[1,0,0] neg_hi:[1,0,0]
	v_pk_fma_f32 v[8:9], v[94:95], v[12:13], v[50:51] op_sel_hi:[1,0,1] neg_lo:[1,0,0] neg_hi:[1,0,0]
	ds_read_b128 v[20:23], v10 offset:4352
	ds_read_b128 v[28:31], v10 offset:4864
	ds_read_b128 v[24:27], v10 offset:4608
	s_waitcnt lgkmcnt(4)
	v_fma_mix_f32 v12, v6, v110, v180 op_sel_hi:[0,1,0]
	v_fma_mix_f32 v12, v7, v110, v12 op_sel:[0,1,0] op_sel_hi:[0,1,0]
	v_fma_mix_f32 v12, v8, v111, v12 op_sel_hi:[0,1,0]
	v_fma_mix_f32 v12, v9, v111, v12 op_sel:[0,1,0] op_sel_hi:[0,1,0]
	v_fma_mix_f32 v54, v6, v90, v180 op_sel_hi:[0,1,0]
	v_fma_mix_f32 v54, v7, v90, v54 op_sel:[0,1,0] op_sel_hi:[0,1,0]
	v_add_f32_dpp v12, v12, v12 row_ror:1 row_mask:0xf bank_mask:0xf bound_ctrl:1
	v_fma_mix_f32 v54, v8, v91, v54 op_sel_hi:[0,1,0]
	v_fma_mix_f32 v54, v9, v91, v54 op_sel:[0,1,0] op_sel_hi:[0,1,0]
	v_add_f32_dpp v12, v12, v12 row_ror:2 row_mask:0xf bank_mask:0xf bound_ctrl:1
	v_pk_fma_f32 v[48:49], v[118:119], v[68:69], v[6:7] op_sel:[0,1,0]
	v_pk_fma_f32 v[50:51], v[120:121], v[68:69], v[8:9] op_sel:[0,1,0]
	v_add_f32_dpp v12, v12, v12 row_ror:4 row_mask:0xf bank_mask:0xf bound_ctrl:1
	s_nop 1
	v_add_f32_dpp v12, v12, v12 row_ror:8 row_mask:0xf bank_mask:0xf bound_ctrl:1
	v_pk_fma_f32 v[6:7], v[114:115], v[12:13], v[48:49] op_sel_hi:[1,0,1] neg_lo:[1,0,0] neg_hi:[1,0,0]
	v_pk_fma_f32 v[8:9], v[116:117], v[12:13], v[50:51] op_sel_hi:[1,0,1] neg_lo:[1,0,0] neg_hi:[1,0,0]
	v_pk_mul_f32 v[6:7], v[6:7], v[106:107]
	v_pk_mul_f32 v[8:9], v[8:9], v[108:109]
	ds_read_b128 v[36:39], v10 offset:5376
	ds_read_b128 v[44:47], v10 offset:5888
	ds_read_b128 v[40:43], v10 offset:5632
	s_waitcnt lgkmcnt(3)
	v_fma_mix_f32 v12, v6, v20, v180 op_sel_hi:[0,1,0]
	v_fma_mix_f32 v12, v7, v20, v12 op_sel:[0,1,0] op_sel_hi:[0,1,0]
	v_fma_mix_f32 v12, v8, v21, v12 op_sel_hi:[0,1,0]
	v_fma_mix_f32 v12, v9, v21, v12 op_sel:[0,1,0] op_sel_hi:[0,1,0]
	v_fma_mix_f32 v55, v6, v112, v180 op_sel_hi:[0,1,0]
	v_fma_mix_f32 v55, v7, v112, v55 op_sel:[0,1,0] op_sel_hi:[0,1,0]
	v_add_f32_dpp v12, v12, v12 row_ror:1 row_mask:0xf bank_mask:0xf bound_ctrl:1
	v_fma_mix_f32 v55, v8, v113, v55 op_sel_hi:[0,1,0]
	v_fma_mix_f32 v55, v9, v113, v55 op_sel:[0,1,0] op_sel_hi:[0,1,0]
	v_add_f32_dpp v12, v12, v12 row_ror:2 row_mask:0xf bank_mask:0xf bound_ctrl:1
	v_pk_fma_f32 v[48:49], v[28:29], v[70:71], v[6:7] op_sel_hi:[1,0,1]
	v_pk_fma_f32 v[50:51], v[30:31], v[70:71], v[8:9] op_sel_hi:[1,0,1]
	v_add_f32_dpp v12, v12, v12 row_ror:4 row_mask:0xf bank_mask:0xf bound_ctrl:1
	s_nop 1
	v_add_f32_dpp v12, v12, v12 row_ror:8 row_mask:0xf bank_mask:0xf bound_ctrl:1
	v_pk_fma_f32 v[6:7], v[24:25], v[12:13], v[48:49] op_sel_hi:[1,0,1] neg_lo:[1,0,0] neg_hi:[1,0,0]
	v_pk_fma_f32 v[8:9], v[26:27], v[12:13], v[50:51] op_sel_hi:[1,0,1] neg_lo:[1,0,0] neg_hi:[1,0,0]
	ds_read_b128 v[88:91], v10 offset:6400
	ds_read_b128 v[96:99], v10 offset:6912
	ds_read_b128 v[92:95], v10 offset:6656
	s_waitcnt lgkmcnt(3)
	v_fma_mix_f32 v12, v6, v36, v180 op_sel_hi:[0,1,0]
	v_fma_mix_f32 v12, v7, v36, v12 op_sel:[0,1,0] op_sel_hi:[0,1,0]
	v_fma_mix_f32 v12, v8, v37, v12 op_sel_hi:[0,1,0]
	v_fma_mix_f32 v12, v9, v37, v12 op_sel:[0,1,0] op_sel_hi:[0,1,0]
	v_fma_mix_f32 v56, v6, v22, v180 op_sel_hi:[0,1,0]
	v_fma_mix_f32 v56, v7, v22, v56 op_sel:[0,1,0] op_sel_hi:[0,1,0]
	v_add_f32_dpp v12, v12, v12 row_ror:1 row_mask:0xf bank_mask:0xf bound_ctrl:1
	v_fma_mix_f32 v56, v8, v23, v56 op_sel_hi:[0,1,0]
	v_fma_mix_f32 v56, v9, v23, v56 op_sel:[0,1,0] op_sel_hi:[0,1,0]
	v_add_f32_dpp v12, v12, v12 row_ror:2 row_mask:0xf bank_mask:0xf bound_ctrl:1
	v_pk_fma_f32 v[48:49], v[44:45], v[70:71], v[6:7] op_sel:[0,1,0]
	v_pk_fma_f32 v[50:51], v[46:47], v[70:71], v[8:9] op_sel:[0,1,0]
	v_add_f32_dpp v12, v12, v12 row_ror:4 row_mask:0xf bank_mask:0xf bound_ctrl:1
	s_nop 1
	v_add_f32_dpp v12, v12, v12 row_ror:8 row_mask:0xf bank_mask:0xf bound_ctrl:1
	v_pk_fma_f32 v[6:7], v[40:41], v[12:13], v[48:49] op_sel_hi:[1,0,1] neg_lo:[1,0,0] neg_hi:[1,0,0]
	v_pk_fma_f32 v[8:9], v[42:43], v[12:13], v[50:51] op_sel_hi:[1,0,1] neg_lo:[1,0,0] neg_hi:[1,0,0]
	ds_read_b128 v[110:113], v10 offset:7424
	ds_read_b128 v[106:109], v10 offset:7168
	ds_read_b128 v[118:121], v10 offset:7936
	ds_read_b128 v[114:117], v10 offset:7680
	ds_read_b128 v[66:69], v11 offset:512
	s_waitcnt lgkmcnt(5)
	v_fma_mix_f32 v12, v6, v88, v180 op_sel_hi:[0,1,0]
	v_fma_mix_f32 v12, v7, v88, v12 op_sel:[0,1,0] op_sel_hi:[0,1,0]
	v_fma_mix_f32 v12, v8, v89, v12 op_sel_hi:[0,1,0]
	v_fma_mix_f32 v12, v9, v89, v12 op_sel:[0,1,0] op_sel_hi:[0,1,0]
	v_fma_mix_f32 v57, v6, v38, v180 op_sel_hi:[0,1,0]
	v_fma_mix_f32 v57, v7, v38, v57 op_sel:[0,1,0] op_sel_hi:[0,1,0]
	v_add_f32_dpp v12, v12, v12 row_ror:1 row_mask:0xf bank_mask:0xf bound_ctrl:1
	v_fma_mix_f32 v57, v8, v39, v57 op_sel_hi:[0,1,0]
	v_fma_mix_f32 v57, v9, v39, v57 op_sel:[0,1,0] op_sel_hi:[0,1,0]
	v_add_f32_dpp v12, v12, v12 row_ror:2 row_mask:0xf bank_mask:0xf bound_ctrl:1
	v_pk_fma_f32 v[48:49], v[96:97], v[72:73], v[6:7] op_sel_hi:[1,0,1]
	v_pk_fma_f32 v[50:51], v[98:99], v[72:73], v[8:9] op_sel_hi:[1,0,1]
	v_add_f32_dpp v12, v12, v12 row_ror:4 row_mask:0xf bank_mask:0xf bound_ctrl:1
	s_nop 1
	v_add_f32_dpp v12, v12, v12 row_ror:8 row_mask:0xf bank_mask:0xf bound_ctrl:1
	v_pk_fma_f32 v[6:7], v[92:93], v[12:13], v[48:49] op_sel_hi:[1,0,1] neg_lo:[1,0,0] neg_hi:[1,0,0]
	v_pk_fma_f32 v[8:9], v[94:95], v[12:13], v[50:51] op_sel_hi:[1,0,1] neg_lo:[1,0,0] neg_hi:[1,0,0]
	ds_read_b128 v[20:23], v10 offset:8448
	ds_read_b128 v[28:31], v10 offset:8960
	ds_read_b128 v[24:27], v10 offset:8704
	s_waitcnt lgkmcnt(4)
	v_fma_mix_f32 v12, v6, v110, v180 op_sel_hi:[0,1,0]
	v_fma_mix_f32 v12, v7, v110, v12 op_sel:[0,1,0] op_sel_hi:[0,1,0]
	v_fma_mix_f32 v12, v8, v111, v12 op_sel_hi:[0,1,0]
	v_fma_mix_f32 v12, v9, v111, v12 op_sel:[0,1,0] op_sel_hi:[0,1,0]
	v_fma_mix_f32 v81, v6, v90, v180 op_sel_hi:[0,1,0]
	v_fma_mix_f32 v81, v7, v90, v81 op_sel:[0,1,0] op_sel_hi:[0,1,0]
	v_add_f32_dpp v12, v12, v12 row_ror:1 row_mask:0xf bank_mask:0xf bound_ctrl:1
	v_fma_mix_f32 v81, v8, v91, v81 op_sel_hi:[0,1,0]
	v_fma_mix_f32 v81, v9, v91, v81 op_sel:[0,1,0] op_sel_hi:[0,1,0]
	v_add_f32_dpp v12, v12, v12 row_ror:2 row_mask:0xf bank_mask:0xf bound_ctrl:1
	v_pk_fma_f32 v[48:49], v[118:119], v[72:73], v[6:7] op_sel:[0,1,0]
	v_pk_fma_f32 v[50:51], v[120:121], v[72:73], v[8:9] op_sel:[0,1,0]
	v_add_f32_dpp v12, v12, v12 row_ror:4 row_mask:0xf bank_mask:0xf bound_ctrl:1
	s_nop 1
	v_add_f32_dpp v12, v12, v12 row_ror:8 row_mask:0xf bank_mask:0xf bound_ctrl:1
	v_pk_fma_f32 v[6:7], v[114:115], v[12:13], v[48:49] op_sel_hi:[1,0,1] neg_lo:[1,0,0] neg_hi:[1,0,0]
	v_pk_fma_f32 v[8:9], v[116:117], v[12:13], v[50:51] op_sel_hi:[1,0,1] neg_lo:[1,0,0] neg_hi:[1,0,0]
	v_pk_mul_f32 v[6:7], v[6:7], v[106:107]
	v_pk_mul_f32 v[8:9], v[8:9], v[108:109]
	ds_read_b128 v[36:39], v10 offset:9472
	ds_read_b128 v[44:47], v10 offset:9984
	ds_read_b128 v[40:43], v10 offset:9728
	s_waitcnt lgkmcnt(3)
	v_fma_mix_f32 v12, v6, v20, v180 op_sel_hi:[0,1,0]
	v_fma_mix_f32 v12, v7, v20, v12 op_sel:[0,1,0] op_sel_hi:[0,1,0]
	v_fma_mix_f32 v12, v8, v21, v12 op_sel_hi:[0,1,0]
	v_fma_mix_f32 v12, v9, v21, v12 op_sel:[0,1,0] op_sel_hi:[0,1,0]
	v_fma_mix_f32 v82, v6, v112, v180 op_sel_hi:[0,1,0]
	v_fma_mix_f32 v82, v7, v112, v82 op_sel:[0,1,0] op_sel_hi:[0,1,0]
	v_add_f32_dpp v12, v12, v12 row_ror:1 row_mask:0xf bank_mask:0xf bound_ctrl:1
	v_fma_mix_f32 v82, v8, v113, v82 op_sel_hi:[0,1,0]
	v_fma_mix_f32 v82, v9, v113, v82 op_sel:[0,1,0] op_sel_hi:[0,1,0]
	v_add_f32_dpp v12, v12, v12 row_ror:2 row_mask:0xf bank_mask:0xf bound_ctrl:1
	v_pk_fma_f32 v[48:49], v[28:29], v[66:67], v[6:7] op_sel_hi:[1,0,1]
	v_pk_fma_f32 v[50:51], v[30:31], v[66:67], v[8:9] op_sel_hi:[1,0,1]
	v_add_f32_dpp v12, v12, v12 row_ror:4 row_mask:0xf bank_mask:0xf bound_ctrl:1
	s_nop 1
	v_add_f32_dpp v12, v12, v12 row_ror:8 row_mask:0xf bank_mask:0xf bound_ctrl:1
	v_pk_fma_f32 v[6:7], v[24:25], v[12:13], v[48:49] op_sel_hi:[1,0,1] neg_lo:[1,0,0] neg_hi:[1,0,0]
	v_pk_fma_f32 v[8:9], v[26:27], v[12:13], v[50:51] op_sel_hi:[1,0,1] neg_lo:[1,0,0] neg_hi:[1,0,0]
	ds_read_b128 v[88:91], v10 offset:10496
	ds_read_b128 v[96:99], v10 offset:11008
	ds_read_b128 v[92:95], v10 offset:10752
	s_waitcnt lgkmcnt(3)
	v_fma_mix_f32 v12, v6, v36, v180 op_sel_hi:[0,1,0]
	v_fma_mix_f32 v12, v7, v36, v12 op_sel:[0,1,0] op_sel_hi:[0,1,0]
	v_fma_mix_f32 v12, v8, v37, v12 op_sel_hi:[0,1,0]
	v_fma_mix_f32 v12, v9, v37, v12 op_sel:[0,1,0] op_sel_hi:[0,1,0]
	v_fma_mix_f32 v83, v6, v22, v180 op_sel_hi:[0,1,0]
	v_fma_mix_f32 v83, v7, v22, v83 op_sel:[0,1,0] op_sel_hi:[0,1,0]
	v_add_f32_dpp v12, v12, v12 row_ror:1 row_mask:0xf bank_mask:0xf bound_ctrl:1
	v_fma_mix_f32 v83, v8, v23, v83 op_sel_hi:[0,1,0]
	v_fma_mix_f32 v83, v9, v23, v83 op_sel:[0,1,0] op_sel_hi:[0,1,0]
	v_add_f32_dpp v12, v12, v12 row_ror:2 row_mask:0xf bank_mask:0xf bound_ctrl:1
	v_pk_fma_f32 v[48:49], v[44:45], v[66:67], v[6:7] op_sel:[0,1,0]
	v_pk_fma_f32 v[50:51], v[46:47], v[66:67], v[8:9] op_sel:[0,1,0]
	v_add_f32_dpp v12, v12, v12 row_ror:4 row_mask:0xf bank_mask:0xf bound_ctrl:1
	s_nop 1
	v_add_f32_dpp v12, v12, v12 row_ror:8 row_mask:0xf bank_mask:0xf bound_ctrl:1
	v_pk_fma_f32 v[6:7], v[40:41], v[12:13], v[48:49] op_sel_hi:[1,0,1] neg_lo:[1,0,0] neg_hi:[1,0,0]
	v_pk_fma_f32 v[8:9], v[42:43], v[12:13], v[50:51] op_sel_hi:[1,0,1] neg_lo:[1,0,0] neg_hi:[1,0,0]
	ds_read_b128 v[110:113], v10 offset:11520
	ds_read_b128 v[106:109], v10 offset:11264
	ds_read_b128 v[118:121], v10 offset:12032
	ds_read_b128 v[114:117], v10 offset:11776
	ds_read_b128 v[70:73], v11 offset:768
	s_waitcnt lgkmcnt(5)
	v_fma_mix_f32 v12, v6, v88, v180 op_sel_hi:[0,1,0]
	v_fma_mix_f32 v12, v7, v88, v12 op_sel:[0,1,0] op_sel_hi:[0,1,0]
	v_fma_mix_f32 v12, v8, v89, v12 op_sel_hi:[0,1,0]
	v_fma_mix_f32 v12, v9, v89, v12 op_sel:[0,1,0] op_sel_hi:[0,1,0]
	v_fma_mix_f32 v100, v6, v38, v180 op_sel_hi:[0,1,0]
	v_fma_mix_f32 v100, v7, v38, v100 op_sel:[0,1,0] op_sel_hi:[0,1,0]
	v_add_f32_dpp v12, v12, v12 row_ror:1 row_mask:0xf bank_mask:0xf bound_ctrl:1
	v_fma_mix_f32 v100, v8, v39, v100 op_sel_hi:[0,1,0]
	v_fma_mix_f32 v100, v9, v39, v100 op_sel:[0,1,0] op_sel_hi:[0,1,0]
	v_add_f32_dpp v12, v12, v12 row_ror:2 row_mask:0xf bank_mask:0xf bound_ctrl:1
	v_pk_fma_f32 v[48:49], v[96:97], v[68:69], v[6:7] op_sel_hi:[1,0,1]
	v_pk_fma_f32 v[50:51], v[98:99], v[68:69], v[8:9] op_sel_hi:[1,0,1]
	v_add_f32_dpp v12, v12, v12 row_ror:4 row_mask:0xf bank_mask:0xf bound_ctrl:1
	s_nop 1
	v_add_f32_dpp v12, v12, v12 row_ror:8 row_mask:0xf bank_mask:0xf bound_ctrl:1
	v_pk_fma_f32 v[6:7], v[92:93], v[12:13], v[48:49] op_sel_hi:[1,0,1] neg_lo:[1,0,0] neg_hi:[1,0,0]
	v_pk_fma_f32 v[8:9], v[94:95], v[12:13], v[50:51] op_sel_hi:[1,0,1] neg_lo:[1,0,0] neg_hi:[1,0,0]
	ds_read_b128 v[20:23], v10 offset:12544
	ds_read_b128 v[28:31], v10 offset:13056
	ds_read_b128 v[24:27], v10 offset:12800
	s_waitcnt lgkmcnt(4)
	v_fma_mix_f32 v12, v6, v110, v180 op_sel_hi:[0,1,0]
	v_fma_mix_f32 v12, v7, v110, v12 op_sel:[0,1,0] op_sel_hi:[0,1,0]
	v_fma_mix_f32 v12, v8, v111, v12 op_sel_hi:[0,1,0]
	v_fma_mix_f32 v12, v9, v111, v12 op_sel:[0,1,0] op_sel_hi:[0,1,0]
	v_fma_mix_f32 v101, v6, v90, v180 op_sel_hi:[0,1,0]
	v_fma_mix_f32 v101, v7, v90, v101 op_sel:[0,1,0] op_sel_hi:[0,1,0]
	v_add_f32_dpp v12, v12, v12 row_ror:1 row_mask:0xf bank_mask:0xf bound_ctrl:1
	v_fma_mix_f32 v101, v8, v91, v101 op_sel_hi:[0,1,0]
	v_fma_mix_f32 v101, v9, v91, v101 op_sel:[0,1,0] op_sel_hi:[0,1,0]
	v_add_f32_dpp v12, v12, v12 row_ror:2 row_mask:0xf bank_mask:0xf bound_ctrl:1
	v_pk_fma_f32 v[48:49], v[118:119], v[68:69], v[6:7] op_sel:[0,1,0]
	v_pk_fma_f32 v[50:51], v[120:121], v[68:69], v[8:9] op_sel:[0,1,0]
	v_add_f32_dpp v12, v12, v12 row_ror:4 row_mask:0xf bank_mask:0xf bound_ctrl:1
	s_nop 1
	v_add_f32_dpp v12, v12, v12 row_ror:8 row_mask:0xf bank_mask:0xf bound_ctrl:1
	v_pk_fma_f32 v[6:7], v[114:115], v[12:13], v[48:49] op_sel_hi:[1,0,1] neg_lo:[1,0,0] neg_hi:[1,0,0]
	v_pk_fma_f32 v[8:9], v[116:117], v[12:13], v[50:51] op_sel_hi:[1,0,1] neg_lo:[1,0,0] neg_hi:[1,0,0]
	v_pk_mul_f32 v[6:7], v[6:7], v[106:107]
	v_pk_mul_f32 v[8:9], v[8:9], v[108:109]
	ds_read_b128 v[36:39], v10 offset:13568
	ds_read_b128 v[44:47], v10 offset:14080
	ds_read_b128 v[40:43], v10 offset:13824
	s_waitcnt lgkmcnt(3)
	v_fma_mix_f32 v12, v6, v20, v180 op_sel_hi:[0,1,0]
	v_fma_mix_f32 v12, v7, v20, v12 op_sel:[0,1,0] op_sel_hi:[0,1,0]
	v_fma_mix_f32 v12, v8, v21, v12 op_sel_hi:[0,1,0]
	v_fma_mix_f32 v12, v9, v21, v12 op_sel:[0,1,0] op_sel_hi:[0,1,0]
	v_fma_mix_f32 v102, v6, v112, v180 op_sel_hi:[0,1,0]
	v_fma_mix_f32 v102, v7, v112, v102 op_sel:[0,1,0] op_sel_hi:[0,1,0]
	v_add_f32_dpp v12, v12, v12 row_ror:1 row_mask:0xf bank_mask:0xf bound_ctrl:1
	v_fma_mix_f32 v102, v8, v113, v102 op_sel_hi:[0,1,0]
	v_fma_mix_f32 v102, v9, v113, v102 op_sel:[0,1,0] op_sel_hi:[0,1,0]
	v_add_f32_dpp v12, v12, v12 row_ror:2 row_mask:0xf bank_mask:0xf bound_ctrl:1
	v_pk_fma_f32 v[48:49], v[28:29], v[70:71], v[6:7] op_sel_hi:[1,0,1]
	v_pk_fma_f32 v[50:51], v[30:31], v[70:71], v[8:9] op_sel_hi:[1,0,1]
	v_add_f32_dpp v12, v12, v12 row_ror:4 row_mask:0xf bank_mask:0xf bound_ctrl:1
	s_nop 1
	v_add_f32_dpp v12, v12, v12 row_ror:8 row_mask:0xf bank_mask:0xf bound_ctrl:1
	v_pk_fma_f32 v[6:7], v[24:25], v[12:13], v[48:49] op_sel_hi:[1,0,1] neg_lo:[1,0,0] neg_hi:[1,0,0]
	v_pk_fma_f32 v[8:9], v[26:27], v[12:13], v[50:51] op_sel_hi:[1,0,1] neg_lo:[1,0,0] neg_hi:[1,0,0]
	ds_read_b128 v[88:91], v10 offset:14592
	ds_read_b128 v[96:99], v10 offset:15104
	ds_read_b128 v[92:95], v10 offset:14848
	s_waitcnt lgkmcnt(3)
	v_fma_mix_f32 v12, v6, v36, v180 op_sel_hi:[0,1,0]
	v_fma_mix_f32 v12, v7, v36, v12 op_sel:[0,1,0] op_sel_hi:[0,1,0]
	v_fma_mix_f32 v12, v8, v37, v12 op_sel_hi:[0,1,0]
	v_fma_mix_f32 v12, v9, v37, v12 op_sel:[0,1,0] op_sel_hi:[0,1,0]
	v_fma_mix_f32 v103, v6, v22, v180 op_sel_hi:[0,1,0]
	v_fma_mix_f32 v103, v7, v22, v103 op_sel:[0,1,0] op_sel_hi:[0,1,0]
	v_add_f32_dpp v12, v12, v12 row_ror:1 row_mask:0xf bank_mask:0xf bound_ctrl:1
	v_fma_mix_f32 v103, v8, v23, v103 op_sel_hi:[0,1,0]
	v_fma_mix_f32 v103, v9, v23, v103 op_sel:[0,1,0] op_sel_hi:[0,1,0]
	v_add_f32_dpp v12, v12, v12 row_ror:2 row_mask:0xf bank_mask:0xf bound_ctrl:1
	v_pk_fma_f32 v[48:49], v[44:45], v[70:71], v[6:7] op_sel:[0,1,0]
	v_pk_fma_f32 v[50:51], v[46:47], v[70:71], v[8:9] op_sel:[0,1,0]
	v_add_f32_dpp v12, v12, v12 row_ror:4 row_mask:0xf bank_mask:0xf bound_ctrl:1
	s_nop 1
	v_add_f32_dpp v12, v12, v12 row_ror:8 row_mask:0xf bank_mask:0xf bound_ctrl:1
	v_pk_fma_f32 v[6:7], v[40:41], v[12:13], v[48:49] op_sel_hi:[1,0,1] neg_lo:[1,0,0] neg_hi:[1,0,0]
	v_pk_fma_f32 v[8:9], v[42:43], v[12:13], v[50:51] op_sel_hi:[1,0,1] neg_lo:[1,0,0] neg_hi:[1,0,0]
	ds_read_b128 v[110:113], v10 offset:15616
	ds_read_b128 v[106:109], v10 offset:15360
	ds_read_b128 v[118:121], v10 offset:16128
	ds_read_b128 v[114:117], v10 offset:15872
	ds_read_b128 v[66:69], v11 offset:1024
	s_waitcnt lgkmcnt(5)
	v_fma_mix_f32 v12, v6, v88, v180 op_sel_hi:[0,1,0]
	v_fma_mix_f32 v12, v7, v88, v12 op_sel:[0,1,0] op_sel_hi:[0,1,0]
	v_fma_mix_f32 v12, v8, v89, v12 op_sel_hi:[0,1,0]
	v_fma_mix_f32 v12, v9, v89, v12 op_sel:[0,1,0] op_sel_hi:[0,1,0]
	v_fma_mix_f32 v104, v6, v38, v180 op_sel_hi:[0,1,0]
	v_fma_mix_f32 v104, v7, v38, v104 op_sel:[0,1,0] op_sel_hi:[0,1,0]
	v_add_f32_dpp v12, v12, v12 row_ror:1 row_mask:0xf bank_mask:0xf bound_ctrl:1
	v_fma_mix_f32 v104, v8, v39, v104 op_sel_hi:[0,1,0]
	v_fma_mix_f32 v104, v9, v39, v104 op_sel:[0,1,0] op_sel_hi:[0,1,0]
	v_add_f32_dpp v12, v12, v12 row_ror:2 row_mask:0xf bank_mask:0xf bound_ctrl:1
	v_pk_fma_f32 v[48:49], v[96:97], v[72:73], v[6:7] op_sel_hi:[1,0,1]
	v_pk_fma_f32 v[50:51], v[98:99], v[72:73], v[8:9] op_sel_hi:[1,0,1]
	v_add_f32_dpp v12, v12, v12 row_ror:4 row_mask:0xf bank_mask:0xf bound_ctrl:1
	s_nop 1
	v_add_f32_dpp v12, v12, v12 row_ror:8 row_mask:0xf bank_mask:0xf bound_ctrl:1
	v_pk_fma_f32 v[6:7], v[92:93], v[12:13], v[48:49] op_sel_hi:[1,0,1] neg_lo:[1,0,0] neg_hi:[1,0,0]
	v_pk_fma_f32 v[8:9], v[94:95], v[12:13], v[50:51] op_sel_hi:[1,0,1] neg_lo:[1,0,0] neg_hi:[1,0,0]
	ds_read_b128 v[20:23], v10 offset:16640
	ds_read_b128 v[28:31], v10 offset:17152
	ds_read_b128 v[24:27], v10 offset:16896
	s_waitcnt lgkmcnt(4)
	v_fma_mix_f32 v12, v6, v110, v180 op_sel_hi:[0,1,0]
	v_fma_mix_f32 v12, v7, v110, v12 op_sel:[0,1,0] op_sel_hi:[0,1,0]
	v_fma_mix_f32 v12, v8, v111, v12 op_sel_hi:[0,1,0]
	v_fma_mix_f32 v12, v9, v111, v12 op_sel:[0,1,0] op_sel_hi:[0,1,0]
	v_fma_mix_f32 v105, v6, v90, v180 op_sel_hi:[0,1,0]
	v_fma_mix_f32 v105, v7, v90, v105 op_sel:[0,1,0] op_sel_hi:[0,1,0]
	v_add_f32_dpp v12, v12, v12 row_ror:1 row_mask:0xf bank_mask:0xf bound_ctrl:1
	v_fma_mix_f32 v105, v8, v91, v105 op_sel_hi:[0,1,0]
	v_fma_mix_f32 v105, v9, v91, v105 op_sel:[0,1,0] op_sel_hi:[0,1,0]
	v_add_f32_dpp v12, v12, v12 row_ror:2 row_mask:0xf bank_mask:0xf bound_ctrl:1
	v_pk_fma_f32 v[48:49], v[118:119], v[72:73], v[6:7] op_sel:[0,1,0]
	v_pk_fma_f32 v[50:51], v[120:121], v[72:73], v[8:9] op_sel:[0,1,0]
	v_add_f32_dpp v12, v12, v12 row_ror:4 row_mask:0xf bank_mask:0xf bound_ctrl:1
	s_nop 1
	v_add_f32_dpp v12, v12, v12 row_ror:8 row_mask:0xf bank_mask:0xf bound_ctrl:1
	v_pk_fma_f32 v[6:7], v[114:115], v[12:13], v[48:49] op_sel_hi:[1,0,1] neg_lo:[1,0,0] neg_hi:[1,0,0]
	v_pk_fma_f32 v[8:9], v[116:117], v[12:13], v[50:51] op_sel_hi:[1,0,1] neg_lo:[1,0,0] neg_hi:[1,0,0]
	v_pk_mul_f32 v[6:7], v[6:7], v[106:107]
	v_pk_mul_f32 v[8:9], v[8:9], v[108:109]
	ds_read_b128 v[36:39], v10 offset:17664
	ds_read_b128 v[44:47], v10 offset:18176
	ds_read_b128 v[40:43], v10 offset:17920
	s_waitcnt lgkmcnt(3)
	v_fma_mix_f32 v12, v6, v20, v180 op_sel_hi:[0,1,0]
	v_fma_mix_f32 v12, v7, v20, v12 op_sel:[0,1,0] op_sel_hi:[0,1,0]
	v_fma_mix_f32 v12, v8, v21, v12 op_sel_hi:[0,1,0]
	v_fma_mix_f32 v12, v9, v21, v12 op_sel:[0,1,0] op_sel_hi:[0,1,0]
	v_fma_mix_f32 v61, v6, v112, v180 op_sel_hi:[0,1,0]
	v_fma_mix_f32 v61, v7, v112, v61 op_sel:[0,1,0] op_sel_hi:[0,1,0]
	v_add_f32_dpp v12, v12, v12 row_ror:1 row_mask:0xf bank_mask:0xf bound_ctrl:1
	v_fma_mix_f32 v61, v8, v113, v61 op_sel_hi:[0,1,0]
	v_fma_mix_f32 v61, v9, v113, v61 op_sel:[0,1,0] op_sel_hi:[0,1,0]
	v_add_f32_dpp v12, v12, v12 row_ror:2 row_mask:0xf bank_mask:0xf bound_ctrl:1
	v_pk_fma_f32 v[48:49], v[28:29], v[66:67], v[6:7] op_sel_hi:[1,0,1]
	v_pk_fma_f32 v[50:51], v[30:31], v[66:67], v[8:9] op_sel_hi:[1,0,1]
	v_add_f32_dpp v12, v12, v12 row_ror:4 row_mask:0xf bank_mask:0xf bound_ctrl:1
	s_nop 1
	v_add_f32_dpp v12, v12, v12 row_ror:8 row_mask:0xf bank_mask:0xf bound_ctrl:1
	v_pk_fma_f32 v[6:7], v[24:25], v[12:13], v[48:49] op_sel_hi:[1,0,1] neg_lo:[1,0,0] neg_hi:[1,0,0]
	v_pk_fma_f32 v[8:9], v[26:27], v[12:13], v[50:51] op_sel_hi:[1,0,1] neg_lo:[1,0,0] neg_hi:[1,0,0]
	ds_read_b128 v[88:91], v10 offset:18688
	ds_read_b128 v[96:99], v10 offset:19200
	ds_read_b128 v[92:95], v10 offset:18944
	s_waitcnt lgkmcnt(3)
	v_fma_mix_f32 v12, v6, v36, v180 op_sel_hi:[0,1,0]
	v_fma_mix_f32 v12, v7, v36, v12 op_sel:[0,1,0] op_sel_hi:[0,1,0]
	v_fma_mix_f32 v12, v8, v37, v12 op_sel_hi:[0,1,0]
	v_fma_mix_f32 v12, v9, v37, v12 op_sel:[0,1,0] op_sel_hi:[0,1,0]
	v_fma_mix_f32 v122, v6, v22, v180 op_sel_hi:[0,1,0]
	v_fma_mix_f32 v122, v7, v22, v122 op_sel:[0,1,0] op_sel_hi:[0,1,0]
	v_add_f32_dpp v12, v12, v12 row_ror:1 row_mask:0xf bank_mask:0xf bound_ctrl:1
	v_fma_mix_f32 v122, v8, v23, v122 op_sel_hi:[0,1,0]
	v_fma_mix_f32 v122, v9, v23, v122 op_sel:[0,1,0] op_sel_hi:[0,1,0]
	v_add_f32_dpp v12, v12, v12 row_ror:2 row_mask:0xf bank_mask:0xf bound_ctrl:1
	v_pk_fma_f32 v[48:49], v[44:45], v[66:67], v[6:7] op_sel:[0,1,0]
	v_pk_fma_f32 v[50:51], v[46:47], v[66:67], v[8:9] op_sel:[0,1,0]
	v_add_f32_dpp v12, v12, v12 row_ror:4 row_mask:0xf bank_mask:0xf bound_ctrl:1
	v_add_f32_dpp v83, v83, v83 row_ror:8 row_mask:0xf bank_mask:0xc
	v_add_f32_dpp v83, v52, v52 row_ror:8 row_mask:0xf bank_mask:0x3
	v_add_f32_dpp v100, v100, v100 row_ror:8 row_mask:0xf bank_mask:0xc
	v_add_f32_dpp v12, v12, v12 row_ror:8 row_mask:0xf bank_mask:0xf bound_ctrl:1
	v_pk_fma_f32 v[6:7], v[40:41], v[12:13], v[48:49] op_sel_hi:[1,0,1] neg_lo:[1,0,0] neg_hi:[1,0,0]
	v_pk_fma_f32 v[8:9], v[42:43], v[12:13], v[50:51] op_sel_hi:[1,0,1] neg_lo:[1,0,0] neg_hi:[1,0,0]
	ds_read_b128 v[110:113], v10 offset:19712
	ds_read_b128 v[106:109], v10 offset:19456
	ds_read_b128 v[118:121], v10 offset:20224
	ds_read_b128 v[114:117], v10 offset:19968
	ds_read_b128 v[70:73], v11 offset:1280
	s_waitcnt lgkmcnt(5)
	v_fma_mix_f32 v12, v6, v88, v180 op_sel_hi:[0,1,0]
	v_fma_mix_f32 v12, v7, v88, v12 op_sel:[0,1,0] op_sel_hi:[0,1,0]
	v_fma_mix_f32 v12, v8, v89, v12 op_sel_hi:[0,1,0]
	v_fma_mix_f32 v12, v9, v89, v12 op_sel:[0,1,0] op_sel_hi:[0,1,0]
	v_fma_mix_f32 v123, v6, v38, v180 op_sel_hi:[0,1,0]
	v_fma_mix_f32 v123, v7, v38, v123 op_sel:[0,1,0] op_sel_hi:[0,1,0]
	v_add_f32_dpp v12, v12, v12 row_ror:1 row_mask:0xf bank_mask:0xf bound_ctrl:1
	v_fma_mix_f32 v123, v8, v39, v123 op_sel_hi:[0,1,0]
	v_fma_mix_f32 v123, v9, v39, v123 op_sel:[0,1,0] op_sel_hi:[0,1,0]
	v_add_f32_dpp v12, v12, v12 row_ror:2 row_mask:0xf bank_mask:0xf bound_ctrl:1
	v_pk_fma_f32 v[48:49], v[96:97], v[68:69], v[6:7] op_sel_hi:[1,0,1]
	v_pk_fma_f32 v[50:51], v[98:99], v[68:69], v[8:9] op_sel_hi:[1,0,1]
	v_add_f32_dpp v12, v12, v12 row_ror:4 row_mask:0xf bank_mask:0xf bound_ctrl:1
	v_add_f32_dpp v100, v53, v53 row_ror:8 row_mask:0xf bank_mask:0x3
	v_add_f32_dpp v101, v101, v101 row_ror:8 row_mask:0xf bank_mask:0xc
	v_add_f32_dpp v101, v54, v54 row_ror:8 row_mask:0xf bank_mask:0x3
	v_add_f32_dpp v12, v12, v12 row_ror:8 row_mask:0xf bank_mask:0xf bound_ctrl:1
	v_pk_fma_f32 v[6:7], v[92:93], v[12:13], v[48:49] op_sel_hi:[1,0,1] neg_lo:[1,0,0] neg_hi:[1,0,0]
	v_pk_fma_f32 v[8:9], v[94:95], v[12:13], v[50:51] op_sel_hi:[1,0,1] neg_lo:[1,0,0] neg_hi:[1,0,0]
	ds_read_b128 v[20:23], v10 offset:20736
	ds_read_b128 v[28:31], v10 offset:21248
	ds_read_b128 v[24:27], v10 offset:20992
	s_waitcnt lgkmcnt(4)
	v_fma_mix_f32 v12, v6, v110, v180 op_sel_hi:[0,1,0]
	v_fma_mix_f32 v12, v7, v110, v12 op_sel:[0,1,0] op_sel_hi:[0,1,0]
	v_fma_mix_f32 v12, v8, v111, v12 op_sel_hi:[0,1,0]
	v_fma_mix_f32 v12, v9, v111, v12 op_sel:[0,1,0] op_sel_hi:[0,1,0]
	v_fma_mix_f32 v124, v6, v90, v180 op_sel_hi:[0,1,0]
	v_fma_mix_f32 v124, v7, v90, v124 op_sel:[0,1,0] op_sel_hi:[0,1,0]
	v_add_f32_dpp v12, v12, v12 row_ror:1 row_mask:0xf bank_mask:0xf bound_ctrl:1
	v_fma_mix_f32 v124, v8, v91, v124 op_sel_hi:[0,1,0]
	v_fma_mix_f32 v124, v9, v91, v124 op_sel:[0,1,0] op_sel_hi:[0,1,0]
	v_add_f32_dpp v12, v12, v12 row_ror:2 row_mask:0xf bank_mask:0xf bound_ctrl:1
	v_pk_fma_f32 v[48:49], v[118:119], v[68:69], v[6:7] op_sel:[0,1,0]
	v_pk_fma_f32 v[50:51], v[120:121], v[68:69], v[8:9] op_sel:[0,1,0]
	v_add_f32_dpp v12, v12, v12 row_ror:4 row_mask:0xf bank_mask:0xf bound_ctrl:1
	v_add_f32_dpp v102, v102, v102 row_ror:8 row_mask:0xf bank_mask:0xc
	v_add_f32_dpp v102, v55, v55 row_ror:8 row_mask:0xf bank_mask:0x3
	v_add_f32_dpp v103, v103, v103 row_ror:8 row_mask:0xf bank_mask:0xc
	v_add_f32_dpp v12, v12, v12 row_ror:8 row_mask:0xf bank_mask:0xf bound_ctrl:1
	v_pk_fma_f32 v[6:7], v[114:115], v[12:13], v[48:49] op_sel_hi:[1,0,1] neg_lo:[1,0,0] neg_hi:[1,0,0]
	v_pk_fma_f32 v[8:9], v[116:117], v[12:13], v[50:51] op_sel_hi:[1,0,1] neg_lo:[1,0,0] neg_hi:[1,0,0]
	v_pk_mul_f32 v[6:7], v[6:7], v[106:107]
	v_pk_mul_f32 v[8:9], v[8:9], v[108:109]
	ds_read_b128 v[36:39], v10 offset:21760
	ds_read_b128 v[44:47], v10 offset:22272
	ds_read_b128 v[40:43], v10 offset:22016
	s_waitcnt lgkmcnt(3)
	v_fma_mix_f32 v12, v6, v20, v180 op_sel_hi:[0,1,0]
	v_fma_mix_f32 v12, v7, v20, v12 op_sel:[0,1,0] op_sel_hi:[0,1,0]
	v_fma_mix_f32 v12, v8, v21, v12 op_sel_hi:[0,1,0]
	v_fma_mix_f32 v12, v9, v21, v12 op_sel:[0,1,0] op_sel_hi:[0,1,0]
	v_fma_mix_f32 v125, v6, v112, v180 op_sel_hi:[0,1,0]
	v_fma_mix_f32 v125, v7, v112, v125 op_sel:[0,1,0] op_sel_hi:[0,1,0]
	v_add_f32_dpp v12, v12, v12 row_ror:1 row_mask:0xf bank_mask:0xf bound_ctrl:1
	v_fma_mix_f32 v125, v8, v113, v125 op_sel_hi:[0,1,0]
	v_fma_mix_f32 v125, v9, v113, v125 op_sel:[0,1,0] op_sel_hi:[0,1,0]
	v_add_f32_dpp v12, v12, v12 row_ror:2 row_mask:0xf bank_mask:0xf bound_ctrl:1
	v_pk_fma_f32 v[48:49], v[28:29], v[70:71], v[6:7] op_sel_hi:[1,0,1]
	v_pk_fma_f32 v[50:51], v[30:31], v[70:71], v[8:9] op_sel_hi:[1,0,1]
	v_add_f32_dpp v12, v12, v12 row_ror:4 row_mask:0xf bank_mask:0xf bound_ctrl:1
	v_add_f32_dpp v103, v56, v56 row_ror:8 row_mask:0xf bank_mask:0x3
	v_add_f32_dpp v104, v104, v104 row_ror:8 row_mask:0xf bank_mask:0xc
	v_add_f32_dpp v104, v57, v57 row_ror:8 row_mask:0xf bank_mask:0x3
	v_add_f32_dpp v12, v12, v12 row_ror:8 row_mask:0xf bank_mask:0xf bound_ctrl:1
	v_pk_fma_f32 v[6:7], v[24:25], v[12:13], v[48:49] op_sel_hi:[1,0,1] neg_lo:[1,0,0] neg_hi:[1,0,0]
	v_pk_fma_f32 v[8:9], v[26:27], v[12:13], v[50:51] op_sel_hi:[1,0,1] neg_lo:[1,0,0] neg_hi:[1,0,0]
	ds_read_b128 v[88:91], v10 offset:22784
	ds_read_b128 v[96:99], v10 offset:23296
	ds_read_b128 v[92:95], v10 offset:23040
	s_waitcnt lgkmcnt(3)
	v_fma_mix_f32 v12, v6, v36, v180 op_sel_hi:[0,1,0]
	v_fma_mix_f32 v12, v7, v36, v12 op_sel:[0,1,0] op_sel_hi:[0,1,0]
	v_fma_mix_f32 v12, v8, v37, v12 op_sel_hi:[0,1,0]
	v_fma_mix_f32 v12, v9, v37, v12 op_sel:[0,1,0] op_sel_hi:[0,1,0]
	v_fma_mix_f32 v126, v6, v22, v180 op_sel_hi:[0,1,0]
	v_fma_mix_f32 v126, v7, v22, v126 op_sel:[0,1,0] op_sel_hi:[0,1,0]
	v_add_f32_dpp v12, v12, v12 row_ror:1 row_mask:0xf bank_mask:0xf bound_ctrl:1
	v_fma_mix_f32 v126, v8, v23, v126 op_sel_hi:[0,1,0]
	v_fma_mix_f32 v126, v9, v23, v126 op_sel:[0,1,0] op_sel_hi:[0,1,0]
	v_add_f32_dpp v12, v12, v12 row_ror:2 row_mask:0xf bank_mask:0xf bound_ctrl:1
	v_pk_fma_f32 v[48:49], v[44:45], v[70:71], v[6:7] op_sel:[0,1,0]
	v_pk_fma_f32 v[50:51], v[46:47], v[70:71], v[8:9] op_sel:[0,1,0]
	v_add_f32_dpp v12, v12, v12 row_ror:4 row_mask:0xf bank_mask:0xf bound_ctrl:1
	v_add_f32_dpp v105, v105, v105 row_ror:8 row_mask:0xf bank_mask:0xc
	v_add_f32_dpp v105, v81, v81 row_ror:8 row_mask:0xf bank_mask:0x3
	v_add_f32_dpp v12, v12, v12 row_ror:8 row_mask:0xf bank_mask:0xf bound_ctrl:1
	v_pk_fma_f32 v[6:7], v[40:41], v[12:13], v[48:49] op_sel_hi:[1,0,1] neg_lo:[1,0,0] neg_hi:[1,0,0]
	v_pk_fma_f32 v[8:9], v[42:43], v[12:13], v[50:51] op_sel_hi:[1,0,1] neg_lo:[1,0,0] neg_hi:[1,0,0]
	ds_read_b128 v[110:113], v10 offset:23808
	ds_read_b128 v[106:109], v10 offset:23552
	ds_read_b128 v[118:121], v10 offset:24320
	ds_read_b128 v[114:117], v10 offset:24064
	ds_read_b128 v[66:69], v11 offset:1536
	s_waitcnt lgkmcnt(5)
	v_fma_mix_f32 v12, v6, v88, v180 op_sel_hi:[0,1,0]
	v_fma_mix_f32 v12, v7, v88, v12 op_sel:[0,1,0] op_sel_hi:[0,1,0]
	v_fma_mix_f32 v12, v8, v89, v12 op_sel_hi:[0,1,0]
	v_fma_mix_f32 v12, v9, v89, v12 op_sel:[0,1,0] op_sel_hi:[0,1,0]
	v_fma_mix_f32 v127, v6, v38, v180 op_sel_hi:[0,1,0]
	v_fma_mix_f32 v127, v7, v38, v127 op_sel:[0,1,0] op_sel_hi:[0,1,0]
	v_add_f32_dpp v12, v12, v12 row_ror:1 row_mask:0xf bank_mask:0xf bound_ctrl:1
	v_fma_mix_f32 v127, v8, v39, v127 op_sel_hi:[0,1,0]
	v_fma_mix_f32 v127, v9, v39, v127 op_sel:[0,1,0] op_sel_hi:[0,1,0]
	v_add_f32_dpp v12, v12, v12 row_ror:2 row_mask:0xf bank_mask:0xf bound_ctrl:1
	v_pk_fma_f32 v[48:49], v[96:97], v[72:73], v[6:7] op_sel_hi:[1,0,1]
	v_pk_fma_f32 v[50:51], v[98:99], v[72:73], v[8:9] op_sel_hi:[1,0,1]
	v_add_f32_dpp v12, v12, v12 row_ror:4 row_mask:0xf bank_mask:0xf bound_ctrl:1
	v_add_f32_dpp v61, v61, v61 row_ror:8 row_mask:0xf bank_mask:0xc
	v_add_f32_dpp v61, v82, v82 row_ror:8 row_mask:0xf bank_mask:0x3
	v_add_f32_dpp v12, v12, v12 row_ror:8 row_mask:0xf bank_mask:0xf bound_ctrl:1
	v_pk_fma_f32 v[6:7], v[92:93], v[12:13], v[48:49] op_sel_hi:[1,0,1] neg_lo:[1,0,0] neg_hi:[1,0,0]
	v_pk_fma_f32 v[8:9], v[94:95], v[12:13], v[50:51] op_sel_hi:[1,0,1] neg_lo:[1,0,0] neg_hi:[1,0,0]
	ds_read_b128 v[20:23], v10 offset:24832
	ds_read_b128 v[28:31], v10 offset:25344
	ds_read_b128 v[24:27], v10 offset:25088
	s_waitcnt lgkmcnt(4)
	v_fma_mix_f32 v12, v6, v110, v180 op_sel_hi:[0,1,0]
	v_fma_mix_f32 v12, v7, v110, v12 op_sel:[0,1,0] op_sel_hi:[0,1,0]
	v_fma_mix_f32 v12, v8, v111, v12 op_sel_hi:[0,1,0]
	v_fma_mix_f32 v12, v9, v111, v12 op_sel:[0,1,0] op_sel_hi:[0,1,0]
	v_fma_mix_f32 v128, v6, v90, v180 op_sel_hi:[0,1,0]
	v_fma_mix_f32 v128, v7, v90, v128 op_sel:[0,1,0] op_sel_hi:[0,1,0]
	v_add_f32_dpp v12, v12, v12 row_ror:1 row_mask:0xf bank_mask:0xf bound_ctrl:1
	v_fma_mix_f32 v128, v8, v91, v128 op_sel_hi:[0,1,0]
	v_fma_mix_f32 v128, v9, v91, v128 op_sel:[0,1,0] op_sel_hi:[0,1,0]
	v_add_f32_dpp v12, v12, v12 row_ror:2 row_mask:0xf bank_mask:0xf bound_ctrl:1
	v_pk_fma_f32 v[48:49], v[118:119], v[72:73], v[6:7] op_sel:[0,1,0]
	v_pk_fma_f32 v[50:51], v[120:121], v[72:73], v[8:9] op_sel:[0,1,0]
	v_add_f32_dpp v12, v12, v12 row_ror:4 row_mask:0xf bank_mask:0xf bound_ctrl:1
	v_add_f32_dpp v103, v103, v103 row_ror:4 row_mask:0xf bank_mask:0xa
	v_add_f32_dpp v103, v83, v83 row_ror:12 row_mask:0xf bank_mask:0x5
	v_add_f32_dpp v104, v104, v104 row_ror:4 row_mask:0xf bank_mask:0xa
	v_add_f32_dpp v12, v12, v12 row_ror:8 row_mask:0xf bank_mask:0xf bound_ctrl:1
	v_pk_fma_f32 v[6:7], v[114:115], v[12:13], v[48:49] op_sel_hi:[1,0,1] neg_lo:[1,0,0] neg_hi:[1,0,0]
	v_pk_fma_f32 v[8:9], v[116:117], v[12:13], v[50:51] op_sel_hi:[1,0,1] neg_lo:[1,0,0] neg_hi:[1,0,0]
	v_pk_mul_f32 v[6:7], v[6:7], v[106:107]
	v_pk_mul_f32 v[8:9], v[8:9], v[108:109]
	ds_read_b128 v[36:39], v10 offset:25856
	ds_read_b128 v[44:47], v10 offset:26368
	ds_read_b128 v[40:43], v10 offset:26112
	s_waitcnt lgkmcnt(3)
	v_fma_mix_f32 v12, v6, v20, v180 op_sel_hi:[0,1,0]
	v_fma_mix_f32 v12, v7, v20, v12 op_sel:[0,1,0] op_sel_hi:[0,1,0]
	v_fma_mix_f32 v12, v8, v21, v12 op_sel_hi:[0,1,0]
	v_fma_mix_f32 v12, v9, v21, v12 op_sel:[0,1,0] op_sel_hi:[0,1,0]
	v_fma_mix_f32 v129, v6, v112, v180 op_sel_hi:[0,1,0]
	v_fma_mix_f32 v129, v7, v112, v129 op_sel:[0,1,0] op_sel_hi:[0,1,0]
	v_add_f32_dpp v12, v12, v12 row_ror:1 row_mask:0xf bank_mask:0xf bound_ctrl:1
	v_fma_mix_f32 v129, v8, v113, v129 op_sel_hi:[0,1,0]
	v_fma_mix_f32 v129, v9, v113, v129 op_sel:[0,1,0] op_sel_hi:[0,1,0]
	v_add_f32_dpp v12, v12, v12 row_ror:2 row_mask:0xf bank_mask:0xf bound_ctrl:1
	v_pk_fma_f32 v[48:49], v[28:29], v[66:67], v[6:7] op_sel_hi:[1,0,1]
	v_pk_fma_f32 v[50:51], v[30:31], v[66:67], v[8:9] op_sel_hi:[1,0,1]
	v_add_f32_dpp v12, v12, v12 row_ror:4 row_mask:0xf bank_mask:0xf bound_ctrl:1
	v_add_f32_dpp v104, v100, v100 row_ror:12 row_mask:0xf bank_mask:0x5
	v_add_f32_dpp v105, v105, v105 row_ror:4 row_mask:0xf bank_mask:0xa
	v_add_f32_dpp v105, v101, v101 row_ror:12 row_mask:0xf bank_mask:0x5
	v_add_f32_dpp v12, v12, v12 row_ror:8 row_mask:0xf bank_mask:0xf bound_ctrl:1
	v_pk_fma_f32 v[6:7], v[24:25], v[12:13], v[48:49] op_sel_hi:[1,0,1] neg_lo:[1,0,0] neg_hi:[1,0,0]
	v_pk_fma_f32 v[8:9], v[26:27], v[12:13], v[50:51] op_sel_hi:[1,0,1] neg_lo:[1,0,0] neg_hi:[1,0,0]
	ds_read_b128 v[88:91], v10 offset:26880
	ds_read_b128 v[96:99], v10 offset:27392
	ds_read_b128 v[92:95], v10 offset:27136
	s_waitcnt lgkmcnt(3)
	v_fma_mix_f32 v12, v6, v36, v180 op_sel_hi:[0,1,0]
	v_fma_mix_f32 v12, v7, v36, v12 op_sel:[0,1,0] op_sel_hi:[0,1,0]
	v_fma_mix_f32 v12, v8, v37, v12 op_sel_hi:[0,1,0]
	v_fma_mix_f32 v12, v9, v37, v12 op_sel:[0,1,0] op_sel_hi:[0,1,0]
	v_fma_mix_f32 v130, v6, v22, v180 op_sel_hi:[0,1,0]
	v_fma_mix_f32 v130, v7, v22, v130 op_sel:[0,1,0] op_sel_hi:[0,1,0]
	v_add_f32_dpp v12, v12, v12 row_ror:1 row_mask:0xf bank_mask:0xf bound_ctrl:1
	v_fma_mix_f32 v130, v8, v23, v130 op_sel_hi:[0,1,0]
	v_fma_mix_f32 v130, v9, v23, v130 op_sel:[0,1,0] op_sel_hi:[0,1,0]
	v_add_f32_dpp v12, v12, v12 row_ror:2 row_mask:0xf bank_mask:0xf bound_ctrl:1
	v_pk_fma_f32 v[48:49], v[44:45], v[66:67], v[6:7] op_sel:[0,1,0]
	v_pk_fma_f32 v[50:51], v[46:47], v[66:67], v[8:9] op_sel:[0,1,0]
	v_add_f32_dpp v12, v12, v12 row_ror:4 row_mask:0xf bank_mask:0xf bound_ctrl:1
	v_add_f32_dpp v61, v61, v61 row_ror:4 row_mask:0xf bank_mask:0xa
	v_add_f32_dpp v61, v102, v102 row_ror:12 row_mask:0xf bank_mask:0x5
	v_add_f32_dpp v12, v12, v12 row_ror:8 row_mask:0xf bank_mask:0xf bound_ctrl:1
	v_pk_fma_f32 v[6:7], v[40:41], v[12:13], v[48:49] op_sel_hi:[1,0,1] neg_lo:[1,0,0] neg_hi:[1,0,0]
	v_pk_fma_f32 v[8:9], v[42:43], v[12:13], v[50:51] op_sel_hi:[1,0,1] neg_lo:[1,0,0] neg_hi:[1,0,0]
	ds_read_b128 v[110:113], v10 offset:27904
	ds_read_b128 v[106:109], v10 offset:27648
	ds_read_b128 v[118:121], v10 offset:28416
	ds_read_b128 v[114:117], v10 offset:28160
	ds_read_b128 v[70:73], v11 offset:1792
	s_waitcnt lgkmcnt(5)
	v_fma_mix_f32 v12, v6, v88, v180 op_sel_hi:[0,1,0]
	v_fma_mix_f32 v12, v7, v88, v12 op_sel:[0,1,0] op_sel_hi:[0,1,0]
	v_fma_mix_f32 v12, v8, v89, v12 op_sel_hi:[0,1,0]
	v_fma_mix_f32 v12, v9, v89, v12 op_sel:[0,1,0] op_sel_hi:[0,1,0]
	v_fma_mix_f32 v131, v6, v38, v180 op_sel_hi:[0,1,0]
	v_fma_mix_f32 v131, v7, v38, v131 op_sel:[0,1,0] op_sel_hi:[0,1,0]
	v_add_f32_dpp v12, v12, v12 row_ror:1 row_mask:0xf bank_mask:0xf bound_ctrl:1
	v_fma_mix_f32 v131, v8, v39, v131 op_sel_hi:[0,1,0]
	v_fma_mix_f32 v131, v9, v39, v131 op_sel:[0,1,0] op_sel_hi:[0,1,0]
	v_add_f32_dpp v12, v12, v12 row_ror:2 row_mask:0xf bank_mask:0xf bound_ctrl:1
	v_pk_fma_f32 v[48:49], v[96:97], v[68:69], v[6:7] op_sel_hi:[1,0,1]
	v_pk_fma_f32 v[50:51], v[98:99], v[68:69], v[8:9] op_sel_hi:[1,0,1]
	v_add_f32_dpp v12, v12, v12 row_ror:4 row_mask:0xf bank_mask:0xf bound_ctrl:1
	v_cndmask_b32_e64 v62, v105, v103, s[38:39]
	v_cndmask_b32_e64 v63, v103, v105, s[38:39]
	v_add_f32_dpp v12, v12, v12 row_ror:8 row_mask:0xf bank_mask:0xf bound_ctrl:1
	v_pk_fma_f32 v[6:7], v[92:93], v[12:13], v[48:49] op_sel_hi:[1,0,1] neg_lo:[1,0,0] neg_hi:[1,0,0]
	v_pk_fma_f32 v[8:9], v[94:95], v[12:13], v[50:51] op_sel_hi:[1,0,1] neg_lo:[1,0,0] neg_hi:[1,0,0]
	ds_read_b128 v[20:23], v10 offset:28928
	ds_read_b128 v[28:31], v10 offset:29440
	ds_read_b128 v[24:27], v10 offset:29184
	s_waitcnt lgkmcnt(4)
	v_fma_mix_f32 v12, v6, v110, v180 op_sel_hi:[0,1,0]
	v_fma_mix_f32 v12, v7, v110, v12 op_sel:[0,1,0] op_sel_hi:[0,1,0]
	v_fma_mix_f32 v12, v8, v111, v12 op_sel_hi:[0,1,0]
	v_fma_mix_f32 v12, v9, v111, v12 op_sel:[0,1,0] op_sel_hi:[0,1,0]
	v_fma_mix_f32 v132, v6, v90, v180 op_sel_hi:[0,1,0]
	v_fma_mix_f32 v132, v7, v90, v132 op_sel:[0,1,0] op_sel_hi:[0,1,0]
	v_add_f32_dpp v12, v12, v12 row_ror:1 row_mask:0xf bank_mask:0xf bound_ctrl:1
	v_fma_mix_f32 v132, v8, v91, v132 op_sel_hi:[0,1,0]
	v_fma_mix_f32 v132, v9, v91, v132 op_sel:[0,1,0] op_sel_hi:[0,1,0]
	v_add_f32_dpp v12, v12, v12 row_ror:2 row_mask:0xf bank_mask:0xf bound_ctrl:1
	v_pk_fma_f32 v[48:49], v[118:119], v[68:69], v[6:7] op_sel:[0,1,0]
	v_pk_fma_f32 v[50:51], v[120:121], v[68:69], v[8:9] op_sel:[0,1,0]
	v_add_f32_dpp v12, v12, v12 row_ror:4 row_mask:0xf bank_mask:0xf bound_ctrl:1
	v_cndmask_b32_e64 v64, v61, v104, s[38:39]
	v_cndmask_b32_e64 v65, v104, v61, s[38:39]
	v_add_f32_dpp v12, v12, v12 row_ror:8 row_mask:0xf bank_mask:0xf bound_ctrl:1
	v_pk_fma_f32 v[6:7], v[114:115], v[12:13], v[48:49] op_sel_hi:[1,0,1] neg_lo:[1,0,0] neg_hi:[1,0,0]
	v_pk_fma_f32 v[8:9], v[116:117], v[12:13], v[50:51] op_sel_hi:[1,0,1] neg_lo:[1,0,0] neg_hi:[1,0,0]
	v_pk_mul_f32 v[6:7], v[6:7], v[106:107]
	v_pk_mul_f32 v[8:9], v[8:9], v[108:109]
	ds_read_b128 v[36:39], v10 offset:29952
	ds_read_b128 v[44:47], v10 offset:30464
	ds_read_b128 v[40:43], v10 offset:30208
	s_waitcnt lgkmcnt(3)
	v_fma_mix_f32 v12, v6, v20, v180 op_sel_hi:[0,1,0]
	v_fma_mix_f32 v12, v7, v20, v12 op_sel:[0,1,0] op_sel_hi:[0,1,0]
	v_fma_mix_f32 v12, v8, v21, v12 op_sel_hi:[0,1,0]
	v_fma_mix_f32 v12, v9, v21, v12 op_sel:[0,1,0] op_sel_hi:[0,1,0]
	v_fma_mix_f32 v133, v6, v112, v180 op_sel_hi:[0,1,0]
	v_fma_mix_f32 v133, v7, v112, v133 op_sel:[0,1,0] op_sel_hi:[0,1,0]
	v_add_f32_dpp v12, v12, v12 row_ror:1 row_mask:0xf bank_mask:0xf bound_ctrl:1
	v_fma_mix_f32 v133, v8, v113, v133 op_sel_hi:[0,1,0]
	v_fma_mix_f32 v133, v9, v113, v133 op_sel:[0,1,0] op_sel_hi:[0,1,0]
	v_add_f32_dpp v12, v12, v12 row_ror:2 row_mask:0xf bank_mask:0xf bound_ctrl:1
	v_pk_fma_f32 v[48:49], v[28:29], v[70:71], v[6:7] op_sel_hi:[1,0,1]
	v_pk_fma_f32 v[50:51], v[30:31], v[70:71], v[8:9] op_sel_hi:[1,0,1]
	v_add_f32_dpp v12, v12, v12 row_ror:4 row_mask:0xf bank_mask:0xf bound_ctrl:1
	v_add_f32_dpp v62, v63, v62 quad_perm:[2,3,0,1] row_mask:0xf bank_mask:0xf bound_ctrl:1
	v_add_f32_dpp v63, v65, v64 quad_perm:[2,3,0,1] row_mask:0xf bank_mask:0xf bound_ctrl:1
	v_add_f32_dpp v12, v12, v12 row_ror:8 row_mask:0xf bank_mask:0xf bound_ctrl:1
	v_pk_fma_f32 v[6:7], v[24:25], v[12:13], v[48:49] op_sel_hi:[1,0,1] neg_lo:[1,0,0] neg_hi:[1,0,0]
	v_pk_fma_f32 v[8:9], v[26:27], v[12:13], v[50:51] op_sel_hi:[1,0,1] neg_lo:[1,0,0] neg_hi:[1,0,0]
	ds_read_b128 v[88:91], v10 offset:30976
	ds_read_b128 v[96:99], v10 offset:31488
	ds_read_b128 v[92:95], v10 offset:31232
	s_waitcnt lgkmcnt(3)
	v_fma_mix_f32 v12, v6, v36, v180 op_sel_hi:[0,1,0]
	v_fma_mix_f32 v12, v7, v36, v12 op_sel:[0,1,0] op_sel_hi:[0,1,0]
	v_fma_mix_f32 v12, v8, v37, v12 op_sel_hi:[0,1,0]
	v_fma_mix_f32 v12, v9, v37, v12 op_sel:[0,1,0] op_sel_hi:[0,1,0]
	v_fma_mix_f32 v134, v6, v22, v180 op_sel_hi:[0,1,0]
	v_fma_mix_f32 v134, v7, v22, v134 op_sel:[0,1,0] op_sel_hi:[0,1,0]
	v_add_f32_dpp v12, v12, v12 row_ror:1 row_mask:0xf bank_mask:0xf bound_ctrl:1
	v_fma_mix_f32 v134, v8, v23, v134 op_sel_hi:[0,1,0]
	v_fma_mix_f32 v134, v9, v23, v134 op_sel:[0,1,0] op_sel_hi:[0,1,0]
	v_add_f32_dpp v12, v12, v12 row_ror:2 row_mask:0xf bank_mask:0xf bound_ctrl:1
	v_pk_fma_f32 v[48:49], v[44:45], v[70:71], v[6:7] op_sel:[0,1,0]
	v_pk_fma_f32 v[50:51], v[46:47], v[70:71], v[8:9] op_sel:[0,1,0]
	v_add_f32_dpp v12, v12, v12 row_ror:4 row_mask:0xf bank_mask:0xf bound_ctrl:1
	v_cndmask_b32_e64 v65, v63, v62, s[40:41]
	v_cndmask_b32_e64 v62, v62, v63, s[40:41]
	v_add_f32_dpp v12, v12, v12 row_ror:8 row_mask:0xf bank_mask:0xf bound_ctrl:1
	v_pk_fma_f32 v[6:7], v[40:41], v[12:13], v[48:49] op_sel_hi:[1,0,1] neg_lo:[1,0,0] neg_hi:[1,0,0]
	v_pk_fma_f32 v[8:9], v[42:43], v[12:13], v[50:51] op_sel_hi:[1,0,1] neg_lo:[1,0,0] neg_hi:[1,0,0]
	ds_read_b128 v[110:113], v10 offset:32000
	ds_read_b128 v[106:109], v10 offset:31744
	ds_read_b128 v[118:121], v10 offset:32512
	ds_read_b128 v[114:117], v10 offset:32256
	ds_read_b128 v[66:69], v11 offset:2048
	s_waitcnt lgkmcnt(5)
	v_fma_mix_f32 v12, v6, v88, v180 op_sel_hi:[0,1,0]
	v_fma_mix_f32 v12, v7, v88, v12 op_sel:[0,1,0] op_sel_hi:[0,1,0]
	v_fma_mix_f32 v12, v8, v89, v12 op_sel_hi:[0,1,0]
	v_fma_mix_f32 v12, v9, v89, v12 op_sel:[0,1,0] op_sel_hi:[0,1,0]
	v_fma_mix_f32 v135, v6, v38, v180 op_sel_hi:[0,1,0]
	v_fma_mix_f32 v135, v7, v38, v135 op_sel:[0,1,0] op_sel_hi:[0,1,0]
	v_add_f32_dpp v12, v12, v12 row_ror:1 row_mask:0xf bank_mask:0xf bound_ctrl:1
	v_fma_mix_f32 v135, v8, v39, v135 op_sel_hi:[0,1,0]
	v_fma_mix_f32 v135, v9, v39, v135 op_sel:[0,1,0] op_sel_hi:[0,1,0]
	v_add_f32_dpp v12, v12, v12 row_ror:2 row_mask:0xf bank_mask:0xf bound_ctrl:1
	v_pk_fma_f32 v[48:49], v[96:97], v[72:73], v[6:7] op_sel_hi:[1,0,1]
	v_pk_fma_f32 v[50:51], v[98:99], v[72:73], v[8:9] op_sel_hi:[1,0,1]
	v_add_f32_dpp v12, v12, v12 row_ror:4 row_mask:0xf bank_mask:0xf bound_ctrl:1
	v_add_f32_dpp v62, v62, v65 quad_perm:[1,0,3,2] row_mask:0xf bank_mask:0xf bound_ctrl:1
	v_cvt_pk_bf16_f32 v62, v62, v62
	v_add_f32_dpp v12, v12, v12 row_ror:8 row_mask:0xf bank_mask:0xf bound_ctrl:1
	v_pk_fma_f32 v[6:7], v[92:93], v[12:13], v[48:49] op_sel_hi:[1,0,1] neg_lo:[1,0,0] neg_hi:[1,0,0]
	v_pk_fma_f32 v[8:9], v[94:95], v[12:13], v[50:51] op_sel_hi:[1,0,1] neg_lo:[1,0,0] neg_hi:[1,0,0]
	ds_read_b128 v[20:23], v10 offset:33024
	ds_read_b128 v[28:31], v10 offset:33536
	ds_read_b128 v[24:27], v10 offset:33280
	s_waitcnt lgkmcnt(4)
	v_fma_mix_f32 v12, v6, v110, v180 op_sel_hi:[0,1,0]
	v_fma_mix_f32 v12, v7, v110, v12 op_sel:[0,1,0] op_sel_hi:[0,1,0]
	v_fma_mix_f32 v12, v8, v111, v12 op_sel_hi:[0,1,0]
	v_fma_mix_f32 v12, v9, v111, v12 op_sel:[0,1,0] op_sel_hi:[0,1,0]
	v_fma_mix_f32 v136, v6, v90, v180 op_sel_hi:[0,1,0]
	v_fma_mix_f32 v136, v7, v90, v136 op_sel:[0,1,0] op_sel_hi:[0,1,0]
	v_add_f32_dpp v12, v12, v12 row_ror:1 row_mask:0xf bank_mask:0xf bound_ctrl:1
	v_fma_mix_f32 v136, v8, v91, v136 op_sel_hi:[0,1,0]
	v_fma_mix_f32 v136, v9, v91, v136 op_sel:[0,1,0] op_sel_hi:[0,1,0]
	v_add_f32_dpp v12, v12, v12 row_ror:2 row_mask:0xf bank_mask:0xf bound_ctrl:1
	v_pk_fma_f32 v[48:49], v[118:119], v[72:73], v[6:7] op_sel:[0,1,0]
	v_pk_fma_f32 v[50:51], v[120:121], v[72:73], v[8:9] op_sel:[0,1,0]
	v_add_f32_dpp v12, v12, v12 row_ror:4 row_mask:0xf bank_mask:0xf bound_ctrl:1
	global_store_short v[2:3], v62, off
	v_lshl_add_u64 v[2:3], v[2:3], 0, s[84:85]
	v_add_f32_dpp v12, v12, v12 row_ror:8 row_mask:0xf bank_mask:0xf bound_ctrl:1
	v_pk_fma_f32 v[6:7], v[114:115], v[12:13], v[48:49] op_sel_hi:[1,0,1] neg_lo:[1,0,0] neg_hi:[1,0,0]
	v_pk_fma_f32 v[8:9], v[116:117], v[12:13], v[50:51] op_sel_hi:[1,0,1] neg_lo:[1,0,0] neg_hi:[1,0,0]
	v_pk_mul_f32 v[6:7], v[6:7], v[106:107]
	v_pk_mul_f32 v[8:9], v[8:9], v[108:109]
	ds_read_b128 v[36:39], v10 offset:34048
	ds_read_b128 v[44:47], v10 offset:34560
	ds_read_b128 v[40:43], v10 offset:34304
	s_waitcnt lgkmcnt(3)
	v_fma_mix_f32 v12, v6, v20, v180 op_sel_hi:[0,1,0]
	v_fma_mix_f32 v12, v7, v20, v12 op_sel:[0,1,0] op_sel_hi:[0,1,0]
	v_fma_mix_f32 v12, v8, v21, v12 op_sel_hi:[0,1,0]
	v_fma_mix_f32 v12, v9, v21, v12 op_sel:[0,1,0] op_sel_hi:[0,1,0]
	v_fma_mix_f32 v137, v6, v112, v180 op_sel_hi:[0,1,0]
	v_fma_mix_f32 v137, v7, v112, v137 op_sel:[0,1,0] op_sel_hi:[0,1,0]
	v_add_f32_dpp v12, v12, v12 row_ror:1 row_mask:0xf bank_mask:0xf bound_ctrl:1
	v_fma_mix_f32 v137, v8, v113, v137 op_sel_hi:[0,1,0]
	v_fma_mix_f32 v137, v9, v113, v137 op_sel:[0,1,0] op_sel_hi:[0,1,0]
	v_add_f32_dpp v12, v12, v12 row_ror:2 row_mask:0xf bank_mask:0xf bound_ctrl:1
	v_pk_fma_f32 v[48:49], v[28:29], v[66:67], v[6:7] op_sel_hi:[1,0,1]
	v_pk_fma_f32 v[50:51], v[30:31], v[66:67], v[8:9] op_sel_hi:[1,0,1]
	v_add_f32_dpp v12, v12, v12 row_ror:4 row_mask:0xf bank_mask:0xf bound_ctrl:1
	s_nop 1
	v_add_f32_dpp v12, v12, v12 row_ror:8 row_mask:0xf bank_mask:0xf bound_ctrl:1
	v_pk_fma_f32 v[6:7], v[24:25], v[12:13], v[48:49] op_sel_hi:[1,0,1] neg_lo:[1,0,0] neg_hi:[1,0,0]
	v_pk_fma_f32 v[8:9], v[26:27], v[12:13], v[50:51] op_sel_hi:[1,0,1] neg_lo:[1,0,0] neg_hi:[1,0,0]
	ds_read_b128 v[88:91], v10 offset:35072
	ds_read_b128 v[96:99], v10 offset:35584
	ds_read_b128 v[92:95], v10 offset:35328
	s_waitcnt lgkmcnt(3)
	v_fma_mix_f32 v12, v6, v36, v180 op_sel_hi:[0,1,0]
	v_fma_mix_f32 v12, v7, v36, v12 op_sel:[0,1,0] op_sel_hi:[0,1,0]
	v_fma_mix_f32 v12, v8, v37, v12 op_sel_hi:[0,1,0]
	v_fma_mix_f32 v12, v9, v37, v12 op_sel:[0,1,0] op_sel_hi:[0,1,0]
	v_fma_mix_f32 v52, v6, v22, v180 op_sel_hi:[0,1,0]
	v_fma_mix_f32 v52, v7, v22, v52 op_sel:[0,1,0] op_sel_hi:[0,1,0]
	v_add_f32_dpp v12, v12, v12 row_ror:1 row_mask:0xf bank_mask:0xf bound_ctrl:1
	v_fma_mix_f32 v52, v8, v23, v52 op_sel_hi:[0,1,0]
	v_fma_mix_f32 v52, v9, v23, v52 op_sel:[0,1,0] op_sel_hi:[0,1,0]
	v_add_f32_dpp v12, v12, v12 row_ror:2 row_mask:0xf bank_mask:0xf bound_ctrl:1
	v_pk_fma_f32 v[48:49], v[44:45], v[66:67], v[6:7] op_sel:[0,1,0]
	v_pk_fma_f32 v[50:51], v[46:47], v[66:67], v[8:9] op_sel:[0,1,0]
	v_add_f32_dpp v12, v12, v12 row_ror:4 row_mask:0xf bank_mask:0xf bound_ctrl:1
	v_add_f32_dpp v130, v130, v130 row_ror:8 row_mask:0xf bank_mask:0xc
	v_add_f32_dpp v130, v122, v122 row_ror:8 row_mask:0xf bank_mask:0x3
	v_add_f32_dpp v131, v131, v131 row_ror:8 row_mask:0xf bank_mask:0xc
	v_add_f32_dpp v12, v12, v12 row_ror:8 row_mask:0xf bank_mask:0xf bound_ctrl:1
	v_pk_fma_f32 v[6:7], v[40:41], v[12:13], v[48:49] op_sel_hi:[1,0,1] neg_lo:[1,0,0] neg_hi:[1,0,0]
	v_pk_fma_f32 v[8:9], v[42:43], v[12:13], v[50:51] op_sel_hi:[1,0,1] neg_lo:[1,0,0] neg_hi:[1,0,0]
	ds_read_b128 v[110:113], v10 offset:36096
	ds_read_b128 v[106:109], v10 offset:35840
	ds_read_b128 v[118:121], v10 offset:36608
	ds_read_b128 v[114:117], v10 offset:36352
	ds_read_b128 v[70:73], v11 offset:2304
	s_waitcnt lgkmcnt(5)
	v_fma_mix_f32 v12, v6, v88, v180 op_sel_hi:[0,1,0]
	v_fma_mix_f32 v12, v7, v88, v12 op_sel:[0,1,0] op_sel_hi:[0,1,0]
	v_fma_mix_f32 v12, v8, v89, v12 op_sel_hi:[0,1,0]
	v_fma_mix_f32 v12, v9, v89, v12 op_sel:[0,1,0] op_sel_hi:[0,1,0]
	v_fma_mix_f32 v53, v6, v38, v180 op_sel_hi:[0,1,0]
	v_fma_mix_f32 v53, v7, v38, v53 op_sel:[0,1,0] op_sel_hi:[0,1,0]
	v_add_f32_dpp v12, v12, v12 row_ror:1 row_mask:0xf bank_mask:0xf bound_ctrl:1
	v_fma_mix_f32 v53, v8, v39, v53 op_sel_hi:[0,1,0]
	v_fma_mix_f32 v53, v9, v39, v53 op_sel:[0,1,0] op_sel_hi:[0,1,0]
	v_add_f32_dpp v12, v12, v12 row_ror:2 row_mask:0xf bank_mask:0xf bound_ctrl:1
	v_pk_fma_f32 v[48:49], v[96:97], v[68:69], v[6:7] op_sel_hi:[1,0,1]
	v_pk_fma_f32 v[50:51], v[98:99], v[68:69], v[8:9] op_sel_hi:[1,0,1]
	v_add_f32_dpp v12, v12, v12 row_ror:4 row_mask:0xf bank_mask:0xf bound_ctrl:1
	v_add_f32_dpp v131, v123, v123 row_ror:8 row_mask:0xf bank_mask:0x3
	v_add_f32_dpp v132, v132, v132 row_ror:8 row_mask:0xf bank_mask:0xc
	v_add_f32_dpp v132, v124, v124 row_ror:8 row_mask:0xf bank_mask:0x3
	v_add_f32_dpp v12, v12, v12 row_ror:8 row_mask:0xf bank_mask:0xf bound_ctrl:1
	v_pk_fma_f32 v[6:7], v[92:93], v[12:13], v[48:49] op_sel_hi:[1,0,1] neg_lo:[1,0,0] neg_hi:[1,0,0]
	v_pk_fma_f32 v[8:9], v[94:95], v[12:13], v[50:51] op_sel_hi:[1,0,1] neg_lo:[1,0,0] neg_hi:[1,0,0]
	ds_read_b128 v[20:23], v10 offset:37120
	ds_read_b128 v[28:31], v10 offset:37632
	ds_read_b128 v[24:27], v10 offset:37376
	s_waitcnt lgkmcnt(4)
	v_fma_mix_f32 v12, v6, v110, v180 op_sel_hi:[0,1,0]
	v_fma_mix_f32 v12, v7, v110, v12 op_sel:[0,1,0] op_sel_hi:[0,1,0]
	v_fma_mix_f32 v12, v8, v111, v12 op_sel_hi:[0,1,0]
	v_fma_mix_f32 v12, v9, v111, v12 op_sel:[0,1,0] op_sel_hi:[0,1,0]
	v_fma_mix_f32 v54, v6, v90, v180 op_sel_hi:[0,1,0]
	v_fma_mix_f32 v54, v7, v90, v54 op_sel:[0,1,0] op_sel_hi:[0,1,0]
	v_add_f32_dpp v12, v12, v12 row_ror:1 row_mask:0xf bank_mask:0xf bound_ctrl:1
	v_fma_mix_f32 v54, v8, v91, v54 op_sel_hi:[0,1,0]
	v_fma_mix_f32 v54, v9, v91, v54 op_sel:[0,1,0] op_sel_hi:[0,1,0]
	v_add_f32_dpp v12, v12, v12 row_ror:2 row_mask:0xf bank_mask:0xf bound_ctrl:1
	v_pk_fma_f32 v[48:49], v[118:119], v[68:69], v[6:7] op_sel:[0,1,0]
	v_pk_fma_f32 v[50:51], v[120:121], v[68:69], v[8:9] op_sel:[0,1,0]
	v_add_f32_dpp v12, v12, v12 row_ror:4 row_mask:0xf bank_mask:0xf bound_ctrl:1
	v_add_f32_dpp v133, v133, v133 row_ror:8 row_mask:0xf bank_mask:0xc
	v_add_f32_dpp v133, v125, v125 row_ror:8 row_mask:0xf bank_mask:0x3
	v_add_f32_dpp v134, v134, v134 row_ror:8 row_mask:0xf bank_mask:0xc
	v_add_f32_dpp v12, v12, v12 row_ror:8 row_mask:0xf bank_mask:0xf bound_ctrl:1
	v_pk_fma_f32 v[6:7], v[114:115], v[12:13], v[48:49] op_sel_hi:[1,0,1] neg_lo:[1,0,0] neg_hi:[1,0,0]
	v_pk_fma_f32 v[8:9], v[116:117], v[12:13], v[50:51] op_sel_hi:[1,0,1] neg_lo:[1,0,0] neg_hi:[1,0,0]
	v_pk_mul_f32 v[6:7], v[6:7], v[106:107]
	v_pk_mul_f32 v[8:9], v[8:9], v[108:109]
	ds_read_b128 v[36:39], v10 offset:38144
	ds_read_b128 v[44:47], v10 offset:38656
	ds_read_b128 v[40:43], v10 offset:38400
	s_waitcnt lgkmcnt(3)
	v_fma_mix_f32 v12, v6, v20, v180 op_sel_hi:[0,1,0]
	v_fma_mix_f32 v12, v7, v20, v12 op_sel:[0,1,0] op_sel_hi:[0,1,0]
	v_fma_mix_f32 v12, v8, v21, v12 op_sel_hi:[0,1,0]
	v_fma_mix_f32 v12, v9, v21, v12 op_sel:[0,1,0] op_sel_hi:[0,1,0]
	v_fma_mix_f32 v55, v6, v112, v180 op_sel_hi:[0,1,0]
	v_fma_mix_f32 v55, v7, v112, v55 op_sel:[0,1,0] op_sel_hi:[0,1,0]
	v_add_f32_dpp v12, v12, v12 row_ror:1 row_mask:0xf bank_mask:0xf bound_ctrl:1
	v_fma_mix_f32 v55, v8, v113, v55 op_sel_hi:[0,1,0]
	v_fma_mix_f32 v55, v9, v113, v55 op_sel:[0,1,0] op_sel_hi:[0,1,0]
	v_add_f32_dpp v12, v12, v12 row_ror:2 row_mask:0xf bank_mask:0xf bound_ctrl:1
	v_pk_fma_f32 v[48:49], v[28:29], v[70:71], v[6:7] op_sel_hi:[1,0,1]
	v_pk_fma_f32 v[50:51], v[30:31], v[70:71], v[8:9] op_sel_hi:[1,0,1]
	v_add_f32_dpp v12, v12, v12 row_ror:4 row_mask:0xf bank_mask:0xf bound_ctrl:1
	v_add_f32_dpp v134, v126, v126 row_ror:8 row_mask:0xf bank_mask:0x3
	v_add_f32_dpp v135, v135, v135 row_ror:8 row_mask:0xf bank_mask:0xc
	v_add_f32_dpp v135, v127, v127 row_ror:8 row_mask:0xf bank_mask:0x3
	v_add_f32_dpp v12, v12, v12 row_ror:8 row_mask:0xf bank_mask:0xf bound_ctrl:1
	v_pk_fma_f32 v[6:7], v[24:25], v[12:13], v[48:49] op_sel_hi:[1,0,1] neg_lo:[1,0,0] neg_hi:[1,0,0]
	v_pk_fma_f32 v[8:9], v[26:27], v[12:13], v[50:51] op_sel_hi:[1,0,1] neg_lo:[1,0,0] neg_hi:[1,0,0]
	ds_read_b128 v[88:91], v10 offset:39168
	ds_read_b128 v[96:99], v10 offset:39680
	ds_read_b128 v[92:95], v10 offset:39424
	s_waitcnt lgkmcnt(3)
	v_fma_mix_f32 v12, v6, v36, v180 op_sel_hi:[0,1,0]
	v_fma_mix_f32 v12, v7, v36, v12 op_sel:[0,1,0] op_sel_hi:[0,1,0]
	v_fma_mix_f32 v12, v8, v37, v12 op_sel_hi:[0,1,0]
	v_fma_mix_f32 v12, v9, v37, v12 op_sel:[0,1,0] op_sel_hi:[0,1,0]
	v_fma_mix_f32 v56, v6, v22, v180 op_sel_hi:[0,1,0]
	v_fma_mix_f32 v56, v7, v22, v56 op_sel:[0,1,0] op_sel_hi:[0,1,0]
	v_add_f32_dpp v12, v12, v12 row_ror:1 row_mask:0xf bank_mask:0xf bound_ctrl:1
	v_fma_mix_f32 v56, v8, v23, v56 op_sel_hi:[0,1,0]
	v_fma_mix_f32 v56, v9, v23, v56 op_sel:[0,1,0] op_sel_hi:[0,1,0]
	v_add_f32_dpp v12, v12, v12 row_ror:2 row_mask:0xf bank_mask:0xf bound_ctrl:1
	v_pk_fma_f32 v[48:49], v[44:45], v[70:71], v[6:7] op_sel:[0,1,0]
	v_pk_fma_f32 v[50:51], v[46:47], v[70:71], v[8:9] op_sel:[0,1,0]
	v_add_f32_dpp v12, v12, v12 row_ror:4 row_mask:0xf bank_mask:0xf bound_ctrl:1
	v_add_f32_dpp v136, v136, v136 row_ror:8 row_mask:0xf bank_mask:0xc
	v_add_f32_dpp v136, v128, v128 row_ror:8 row_mask:0xf bank_mask:0x3
	v_add_f32_dpp v12, v12, v12 row_ror:8 row_mask:0xf bank_mask:0xf bound_ctrl:1
	v_pk_fma_f32 v[6:7], v[40:41], v[12:13], v[48:49] op_sel_hi:[1,0,1] neg_lo:[1,0,0] neg_hi:[1,0,0]
	v_pk_fma_f32 v[8:9], v[42:43], v[12:13], v[50:51] op_sel_hi:[1,0,1] neg_lo:[1,0,0] neg_hi:[1,0,0]
	ds_read_b128 v[110:113], v10 offset:40192
	ds_read_b128 v[106:109], v10 offset:39936
	ds_read_b128 v[118:121], v10 offset:40704
	ds_read_b128 v[114:117], v10 offset:40448
	ds_read_b128 v[66:69], v11 offset:2560
	s_waitcnt lgkmcnt(5)
	v_fma_mix_f32 v12, v6, v88, v180 op_sel_hi:[0,1,0]
	v_fma_mix_f32 v12, v7, v88, v12 op_sel:[0,1,0] op_sel_hi:[0,1,0]
	v_fma_mix_f32 v12, v8, v89, v12 op_sel_hi:[0,1,0]
	v_fma_mix_f32 v12, v9, v89, v12 op_sel:[0,1,0] op_sel_hi:[0,1,0]
	v_fma_mix_f32 v57, v6, v38, v180 op_sel_hi:[0,1,0]
	v_fma_mix_f32 v57, v7, v38, v57 op_sel:[0,1,0] op_sel_hi:[0,1,0]
	v_add_f32_dpp v12, v12, v12 row_ror:1 row_mask:0xf bank_mask:0xf bound_ctrl:1
	v_fma_mix_f32 v57, v8, v39, v57 op_sel_hi:[0,1,0]
	v_fma_mix_f32 v57, v9, v39, v57 op_sel:[0,1,0] op_sel_hi:[0,1,0]
	v_add_f32_dpp v12, v12, v12 row_ror:2 row_mask:0xf bank_mask:0xf bound_ctrl:1
	v_pk_fma_f32 v[48:49], v[96:97], v[72:73], v[6:7] op_sel_hi:[1,0,1]
	v_pk_fma_f32 v[50:51], v[98:99], v[72:73], v[8:9] op_sel_hi:[1,0,1]
	v_add_f32_dpp v12, v12, v12 row_ror:4 row_mask:0xf bank_mask:0xf bound_ctrl:1
	v_add_f32_dpp v137, v137, v137 row_ror:8 row_mask:0xf bank_mask:0xc
	v_add_f32_dpp v137, v129, v129 row_ror:8 row_mask:0xf bank_mask:0x3
	v_add_f32_dpp v12, v12, v12 row_ror:8 row_mask:0xf bank_mask:0xf bound_ctrl:1
	v_pk_fma_f32 v[6:7], v[92:93], v[12:13], v[48:49] op_sel_hi:[1,0,1] neg_lo:[1,0,0] neg_hi:[1,0,0]
	v_pk_fma_f32 v[8:9], v[94:95], v[12:13], v[50:51] op_sel_hi:[1,0,1] neg_lo:[1,0,0] neg_hi:[1,0,0]
	ds_read_b128 v[20:23], v10 offset:41216
	ds_read_b128 v[28:31], v10 offset:41728
	ds_read_b128 v[24:27], v10 offset:41472
	s_waitcnt lgkmcnt(4)
	v_fma_mix_f32 v12, v6, v110, v180 op_sel_hi:[0,1,0]
	v_fma_mix_f32 v12, v7, v110, v12 op_sel:[0,1,0] op_sel_hi:[0,1,0]
	v_fma_mix_f32 v12, v8, v111, v12 op_sel_hi:[0,1,0]
	v_fma_mix_f32 v12, v9, v111, v12 op_sel:[0,1,0] op_sel_hi:[0,1,0]
	v_fma_mix_f32 v81, v6, v90, v180 op_sel_hi:[0,1,0]
	v_fma_mix_f32 v81, v7, v90, v81 op_sel:[0,1,0] op_sel_hi:[0,1,0]
	v_add_f32_dpp v12, v12, v12 row_ror:1 row_mask:0xf bank_mask:0xf bound_ctrl:1
	v_fma_mix_f32 v81, v8, v91, v81 op_sel_hi:[0,1,0]
	v_fma_mix_f32 v81, v9, v91, v81 op_sel:[0,1,0] op_sel_hi:[0,1,0]
	v_add_f32_dpp v12, v12, v12 row_ror:2 row_mask:0xf bank_mask:0xf bound_ctrl:1
	v_pk_fma_f32 v[48:49], v[118:119], v[72:73], v[6:7] op_sel:[0,1,0]
	v_pk_fma_f32 v[50:51], v[120:121], v[72:73], v[8:9] op_sel:[0,1,0]
	v_add_f32_dpp v12, v12, v12 row_ror:4 row_mask:0xf bank_mask:0xf bound_ctrl:1
	v_add_f32_dpp v134, v134, v134 row_ror:4 row_mask:0xf bank_mask:0xa
	v_add_f32_dpp v134, v130, v130 row_ror:12 row_mask:0xf bank_mask:0x5
	v_add_f32_dpp v135, v135, v135 row_ror:4 row_mask:0xf bank_mask:0xa
	v_add_f32_dpp v12, v12, v12 row_ror:8 row_mask:0xf bank_mask:0xf bound_ctrl:1
	v_pk_fma_f32 v[6:7], v[114:115], v[12:13], v[48:49] op_sel_hi:[1,0,1] neg_lo:[1,0,0] neg_hi:[1,0,0]
	v_pk_fma_f32 v[8:9], v[116:117], v[12:13], v[50:51] op_sel_hi:[1,0,1] neg_lo:[1,0,0] neg_hi:[1,0,0]
	v_pk_mul_f32 v[6:7], v[6:7], v[106:107]
	v_pk_mul_f32 v[8:9], v[8:9], v[108:109]
	ds_read_b128 v[36:39], v10 offset:42240
	ds_read_b128 v[44:47], v10 offset:42752
	ds_read_b128 v[40:43], v10 offset:42496
	s_waitcnt lgkmcnt(3)
	v_fma_mix_f32 v12, v6, v20, v180 op_sel_hi:[0,1,0]
	v_fma_mix_f32 v12, v7, v20, v12 op_sel:[0,1,0] op_sel_hi:[0,1,0]
	v_fma_mix_f32 v12, v8, v21, v12 op_sel_hi:[0,1,0]
	v_fma_mix_f32 v12, v9, v21, v12 op_sel:[0,1,0] op_sel_hi:[0,1,0]
	v_fma_mix_f32 v82, v6, v112, v180 op_sel_hi:[0,1,0]
	v_fma_mix_f32 v82, v7, v112, v82 op_sel:[0,1,0] op_sel_hi:[0,1,0]
	v_add_f32_dpp v12, v12, v12 row_ror:1 row_mask:0xf bank_mask:0xf bound_ctrl:1
	v_fma_mix_f32 v82, v8, v113, v82 op_sel_hi:[0,1,0]
	v_fma_mix_f32 v82, v9, v113, v82 op_sel:[0,1,0] op_sel_hi:[0,1,0]
	v_add_f32_dpp v12, v12, v12 row_ror:2 row_mask:0xf bank_mask:0xf bound_ctrl:1
	v_pk_fma_f32 v[48:49], v[28:29], v[66:67], v[6:7] op_sel_hi:[1,0,1]
	v_pk_fma_f32 v[50:51], v[30:31], v[66:67], v[8:9] op_sel_hi:[1,0,1]
	v_add_f32_dpp v12, v12, v12 row_ror:4 row_mask:0xf bank_mask:0xf bound_ctrl:1
	v_add_f32_dpp v135, v131, v131 row_ror:12 row_mask:0xf bank_mask:0x5
	v_add_f32_dpp v136, v136, v136 row_ror:4 row_mask:0xf bank_mask:0xa
	v_add_f32_dpp v136, v132, v132 row_ror:12 row_mask:0xf bank_mask:0x5
	v_add_f32_dpp v12, v12, v12 row_ror:8 row_mask:0xf bank_mask:0xf bound_ctrl:1
	v_pk_fma_f32 v[6:7], v[24:25], v[12:13], v[48:49] op_sel_hi:[1,0,1] neg_lo:[1,0,0] neg_hi:[1,0,0]
	v_pk_fma_f32 v[8:9], v[26:27], v[12:13], v[50:51] op_sel_hi:[1,0,1] neg_lo:[1,0,0] neg_hi:[1,0,0]
	ds_read_b128 v[88:91], v10 offset:43264
	ds_read_b128 v[96:99], v10 offset:43776
	ds_read_b128 v[92:95], v10 offset:43520
	s_waitcnt lgkmcnt(3)
	v_fma_mix_f32 v12, v6, v36, v180 op_sel_hi:[0,1,0]
	v_fma_mix_f32 v12, v7, v36, v12 op_sel:[0,1,0] op_sel_hi:[0,1,0]
	v_fma_mix_f32 v12, v8, v37, v12 op_sel_hi:[0,1,0]
	v_fma_mix_f32 v12, v9, v37, v12 op_sel:[0,1,0] op_sel_hi:[0,1,0]
	v_fma_mix_f32 v83, v6, v22, v180 op_sel_hi:[0,1,0]
	v_fma_mix_f32 v83, v7, v22, v83 op_sel:[0,1,0] op_sel_hi:[0,1,0]
	v_add_f32_dpp v12, v12, v12 row_ror:1 row_mask:0xf bank_mask:0xf bound_ctrl:1
	v_fma_mix_f32 v83, v8, v23, v83 op_sel_hi:[0,1,0]
	v_fma_mix_f32 v83, v9, v23, v83 op_sel:[0,1,0] op_sel_hi:[0,1,0]
	v_add_f32_dpp v12, v12, v12 row_ror:2 row_mask:0xf bank_mask:0xf bound_ctrl:1
	v_pk_fma_f32 v[48:49], v[44:45], v[66:67], v[6:7] op_sel:[0,1,0]
	v_pk_fma_f32 v[50:51], v[46:47], v[66:67], v[8:9] op_sel:[0,1,0]
	v_add_f32_dpp v12, v12, v12 row_ror:4 row_mask:0xf bank_mask:0xf bound_ctrl:1
	v_add_f32_dpp v137, v137, v137 row_ror:4 row_mask:0xf bank_mask:0xa
	v_add_f32_dpp v137, v133, v133 row_ror:12 row_mask:0xf bank_mask:0x5
	v_add_f32_dpp v12, v12, v12 row_ror:8 row_mask:0xf bank_mask:0xf bound_ctrl:1
	v_pk_fma_f32 v[6:7], v[40:41], v[12:13], v[48:49] op_sel_hi:[1,0,1] neg_lo:[1,0,0] neg_hi:[1,0,0]
	v_pk_fma_f32 v[8:9], v[42:43], v[12:13], v[50:51] op_sel_hi:[1,0,1] neg_lo:[1,0,0] neg_hi:[1,0,0]
	ds_read_b128 v[110:113], v10 offset:44288
	ds_read_b128 v[106:109], v10 offset:44032
	ds_read_b128 v[118:121], v10 offset:44800
	ds_read_b128 v[114:117], v10 offset:44544
	ds_read_b128 v[70:73], v11 offset:2816
	s_waitcnt lgkmcnt(5)
	v_fma_mix_f32 v12, v6, v88, v180 op_sel_hi:[0,1,0]
	v_fma_mix_f32 v12, v7, v88, v12 op_sel:[0,1,0] op_sel_hi:[0,1,0]
	v_fma_mix_f32 v12, v8, v89, v12 op_sel_hi:[0,1,0]
	v_fma_mix_f32 v12, v9, v89, v12 op_sel:[0,1,0] op_sel_hi:[0,1,0]
	v_fma_mix_f32 v100, v6, v38, v180 op_sel_hi:[0,1,0]
	v_fma_mix_f32 v100, v7, v38, v100 op_sel:[0,1,0] op_sel_hi:[0,1,0]
	v_add_f32_dpp v12, v12, v12 row_ror:1 row_mask:0xf bank_mask:0xf bound_ctrl:1
	v_fma_mix_f32 v100, v8, v39, v100 op_sel_hi:[0,1,0]
	v_fma_mix_f32 v100, v9, v39, v100 op_sel:[0,1,0] op_sel_hi:[0,1,0]
	v_add_f32_dpp v12, v12, v12 row_ror:2 row_mask:0xf bank_mask:0xf bound_ctrl:1
	v_pk_fma_f32 v[48:49], v[96:97], v[68:69], v[6:7] op_sel_hi:[1,0,1]
	v_pk_fma_f32 v[50:51], v[98:99], v[68:69], v[8:9] op_sel_hi:[1,0,1]
	v_add_f32_dpp v12, v12, v12 row_ror:4 row_mask:0xf bank_mask:0xf bound_ctrl:1
	v_cndmask_b32_e64 v62, v136, v134, s[38:39]
	v_cndmask_b32_e64 v63, v134, v136, s[38:39]
	v_add_f32_dpp v12, v12, v12 row_ror:8 row_mask:0xf bank_mask:0xf bound_ctrl:1
	v_pk_fma_f32 v[6:7], v[92:93], v[12:13], v[48:49] op_sel_hi:[1,0,1] neg_lo:[1,0,0] neg_hi:[1,0,0]
	v_pk_fma_f32 v[8:9], v[94:95], v[12:13], v[50:51] op_sel_hi:[1,0,1] neg_lo:[1,0,0] neg_hi:[1,0,0]
	ds_read_b128 v[20:23], v10 offset:45312
	ds_read_b128 v[28:31], v10 offset:45824
	ds_read_b128 v[24:27], v10 offset:45568
	s_waitcnt lgkmcnt(4)
	v_fma_mix_f32 v12, v6, v110, v180 op_sel_hi:[0,1,0]
	v_fma_mix_f32 v12, v7, v110, v12 op_sel:[0,1,0] op_sel_hi:[0,1,0]
	v_fma_mix_f32 v12, v8, v111, v12 op_sel_hi:[0,1,0]
	v_fma_mix_f32 v12, v9, v111, v12 op_sel:[0,1,0] op_sel_hi:[0,1,0]
	v_fma_mix_f32 v101, v6, v90, v180 op_sel_hi:[0,1,0]
	v_fma_mix_f32 v101, v7, v90, v101 op_sel:[0,1,0] op_sel_hi:[0,1,0]
	v_add_f32_dpp v12, v12, v12 row_ror:1 row_mask:0xf bank_mask:0xf bound_ctrl:1
	v_fma_mix_f32 v101, v8, v91, v101 op_sel_hi:[0,1,0]
	v_fma_mix_f32 v101, v9, v91, v101 op_sel:[0,1,0] op_sel_hi:[0,1,0]
	v_add_f32_dpp v12, v12, v12 row_ror:2 row_mask:0xf bank_mask:0xf bound_ctrl:1
	v_pk_fma_f32 v[48:49], v[118:119], v[68:69], v[6:7] op_sel:[0,1,0]
	v_pk_fma_f32 v[50:51], v[120:121], v[68:69], v[8:9] op_sel:[0,1,0]
	v_add_f32_dpp v12, v12, v12 row_ror:4 row_mask:0xf bank_mask:0xf bound_ctrl:1
	v_cndmask_b32_e64 v64, v137, v135, s[38:39]
	v_cndmask_b32_e64 v65, v135, v137, s[38:39]
	v_add_f32_dpp v12, v12, v12 row_ror:8 row_mask:0xf bank_mask:0xf bound_ctrl:1
	v_pk_fma_f32 v[6:7], v[114:115], v[12:13], v[48:49] op_sel_hi:[1,0,1] neg_lo:[1,0,0] neg_hi:[1,0,0]
	v_pk_fma_f32 v[8:9], v[116:117], v[12:13], v[50:51] op_sel_hi:[1,0,1] neg_lo:[1,0,0] neg_hi:[1,0,0]
	v_pk_mul_f32 v[6:7], v[6:7], v[106:107]
	v_pk_mul_f32 v[8:9], v[8:9], v[108:109]
	ds_read_b128 v[36:39], v10 offset:46336
	ds_read_b128 v[44:47], v10 offset:46848
	ds_read_b128 v[40:43], v10 offset:46592
	s_waitcnt lgkmcnt(3)
	v_fma_mix_f32 v12, v6, v20, v180 op_sel_hi:[0,1,0]
	v_fma_mix_f32 v12, v7, v20, v12 op_sel:[0,1,0] op_sel_hi:[0,1,0]
	v_fma_mix_f32 v12, v8, v21, v12 op_sel_hi:[0,1,0]
	v_fma_mix_f32 v12, v9, v21, v12 op_sel:[0,1,0] op_sel_hi:[0,1,0]
	v_fma_mix_f32 v102, v6, v112, v180 op_sel_hi:[0,1,0]
	v_fma_mix_f32 v102, v7, v112, v102 op_sel:[0,1,0] op_sel_hi:[0,1,0]
	v_add_f32_dpp v12, v12, v12 row_ror:1 row_mask:0xf bank_mask:0xf bound_ctrl:1
	v_fma_mix_f32 v102, v8, v113, v102 op_sel_hi:[0,1,0]
	v_fma_mix_f32 v102, v9, v113, v102 op_sel:[0,1,0] op_sel_hi:[0,1,0]
	v_add_f32_dpp v12, v12, v12 row_ror:2 row_mask:0xf bank_mask:0xf bound_ctrl:1
	v_pk_fma_f32 v[48:49], v[28:29], v[70:71], v[6:7] op_sel_hi:[1,0,1]
	v_pk_fma_f32 v[50:51], v[30:31], v[70:71], v[8:9] op_sel_hi:[1,0,1]
	v_add_f32_dpp v12, v12, v12 row_ror:4 row_mask:0xf bank_mask:0xf bound_ctrl:1
	v_add_f32_dpp v62, v63, v62 quad_perm:[2,3,0,1] row_mask:0xf bank_mask:0xf bound_ctrl:1
	v_add_f32_dpp v63, v65, v64 quad_perm:[2,3,0,1] row_mask:0xf bank_mask:0xf bound_ctrl:1
	v_add_f32_dpp v12, v12, v12 row_ror:8 row_mask:0xf bank_mask:0xf bound_ctrl:1
	v_pk_fma_f32 v[6:7], v[24:25], v[12:13], v[48:49] op_sel_hi:[1,0,1] neg_lo:[1,0,0] neg_hi:[1,0,0]
	v_pk_fma_f32 v[8:9], v[26:27], v[12:13], v[50:51] op_sel_hi:[1,0,1] neg_lo:[1,0,0] neg_hi:[1,0,0]
	ds_read_b128 v[88:91], v10 offset:47360
	ds_read_b128 v[96:99], v10 offset:47872
	ds_read_b128 v[92:95], v10 offset:47616
	s_waitcnt lgkmcnt(3)
	v_fma_mix_f32 v12, v6, v36, v180 op_sel_hi:[0,1,0]
	v_fma_mix_f32 v12, v7, v36, v12 op_sel:[0,1,0] op_sel_hi:[0,1,0]
	v_fma_mix_f32 v12, v8, v37, v12 op_sel_hi:[0,1,0]
	v_fma_mix_f32 v12, v9, v37, v12 op_sel:[0,1,0] op_sel_hi:[0,1,0]
	v_fma_mix_f32 v103, v6, v22, v180 op_sel_hi:[0,1,0]
	v_fma_mix_f32 v103, v7, v22, v103 op_sel:[0,1,0] op_sel_hi:[0,1,0]
	v_add_f32_dpp v12, v12, v12 row_ror:1 row_mask:0xf bank_mask:0xf bound_ctrl:1
	v_fma_mix_f32 v103, v8, v23, v103 op_sel_hi:[0,1,0]
	v_fma_mix_f32 v103, v9, v23, v103 op_sel:[0,1,0] op_sel_hi:[0,1,0]
	v_add_f32_dpp v12, v12, v12 row_ror:2 row_mask:0xf bank_mask:0xf bound_ctrl:1
	v_pk_fma_f32 v[48:49], v[44:45], v[70:71], v[6:7] op_sel:[0,1,0]
	v_pk_fma_f32 v[50:51], v[46:47], v[70:71], v[8:9] op_sel:[0,1,0]
	v_add_f32_dpp v12, v12, v12 row_ror:4 row_mask:0xf bank_mask:0xf bound_ctrl:1
	v_cndmask_b32_e64 v65, v63, v62, s[40:41]
	v_cndmask_b32_e64 v62, v62, v63, s[40:41]
	v_add_f32_dpp v12, v12, v12 row_ror:8 row_mask:0xf bank_mask:0xf bound_ctrl:1
	v_pk_fma_f32 v[6:7], v[40:41], v[12:13], v[48:49] op_sel_hi:[1,0,1] neg_lo:[1,0,0] neg_hi:[1,0,0]
	v_pk_fma_f32 v[8:9], v[42:43], v[12:13], v[50:51] op_sel_hi:[1,0,1] neg_lo:[1,0,0] neg_hi:[1,0,0]
	ds_read_b128 v[110:113], v10 offset:48384
	ds_read_b128 v[106:109], v10 offset:48128
	ds_read_b128 v[118:121], v10 offset:48896
	ds_read_b128 v[114:117], v10 offset:48640
	ds_read_b128 v[66:69], v11 offset:3072
	s_waitcnt lgkmcnt(5)
	v_fma_mix_f32 v12, v6, v88, v180 op_sel_hi:[0,1,0]
	v_fma_mix_f32 v12, v7, v88, v12 op_sel:[0,1,0] op_sel_hi:[0,1,0]
	v_fma_mix_f32 v12, v8, v89, v12 op_sel_hi:[0,1,0]
	v_fma_mix_f32 v12, v9, v89, v12 op_sel:[0,1,0] op_sel_hi:[0,1,0]
	v_fma_mix_f32 v104, v6, v38, v180 op_sel_hi:[0,1,0]
	v_fma_mix_f32 v104, v7, v38, v104 op_sel:[0,1,0] op_sel_hi:[0,1,0]
	v_add_f32_dpp v12, v12, v12 row_ror:1 row_mask:0xf bank_mask:0xf bound_ctrl:1
	v_fma_mix_f32 v104, v8, v39, v104 op_sel_hi:[0,1,0]
	v_fma_mix_f32 v104, v9, v39, v104 op_sel:[0,1,0] op_sel_hi:[0,1,0]
	v_add_f32_dpp v12, v12, v12 row_ror:2 row_mask:0xf bank_mask:0xf bound_ctrl:1
	v_pk_fma_f32 v[48:49], v[96:97], v[72:73], v[6:7] op_sel_hi:[1,0,1]
	v_pk_fma_f32 v[50:51], v[98:99], v[72:73], v[8:9] op_sel_hi:[1,0,1]
	v_add_f32_dpp v12, v12, v12 row_ror:4 row_mask:0xf bank_mask:0xf bound_ctrl:1
	v_add_f32_dpp v62, v62, v65 quad_perm:[1,0,3,2] row_mask:0xf bank_mask:0xf bound_ctrl:1
	v_cvt_pk_bf16_f32 v62, v62, v62
	v_add_f32_dpp v12, v12, v12 row_ror:8 row_mask:0xf bank_mask:0xf bound_ctrl:1
	v_pk_fma_f32 v[6:7], v[92:93], v[12:13], v[48:49] op_sel_hi:[1,0,1] neg_lo:[1,0,0] neg_hi:[1,0,0]
	v_pk_fma_f32 v[8:9], v[94:95], v[12:13], v[50:51] op_sel_hi:[1,0,1] neg_lo:[1,0,0] neg_hi:[1,0,0]
	ds_read_b128 v[20:23], v10 offset:49408
	ds_read_b128 v[28:31], v10 offset:49920
	ds_read_b128 v[24:27], v10 offset:49664
	s_waitcnt lgkmcnt(4)
	v_fma_mix_f32 v12, v6, v110, v180 op_sel_hi:[0,1,0]
	v_fma_mix_f32 v12, v7, v110, v12 op_sel:[0,1,0] op_sel_hi:[0,1,0]
	v_fma_mix_f32 v12, v8, v111, v12 op_sel_hi:[0,1,0]
	v_fma_mix_f32 v12, v9, v111, v12 op_sel:[0,1,0] op_sel_hi:[0,1,0]
	v_fma_mix_f32 v105, v6, v90, v180 op_sel_hi:[0,1,0]
	v_fma_mix_f32 v105, v7, v90, v105 op_sel:[0,1,0] op_sel_hi:[0,1,0]
	v_add_f32_dpp v12, v12, v12 row_ror:1 row_mask:0xf bank_mask:0xf bound_ctrl:1
	v_fma_mix_f32 v105, v8, v91, v105 op_sel_hi:[0,1,0]
	v_fma_mix_f32 v105, v9, v91, v105 op_sel:[0,1,0] op_sel_hi:[0,1,0]
	v_add_f32_dpp v12, v12, v12 row_ror:2 row_mask:0xf bank_mask:0xf bound_ctrl:1
	v_pk_fma_f32 v[48:49], v[118:119], v[72:73], v[6:7] op_sel:[0,1,0]
	v_pk_fma_f32 v[50:51], v[120:121], v[72:73], v[8:9] op_sel:[0,1,0]
	v_add_f32_dpp v12, v12, v12 row_ror:4 row_mask:0xf bank_mask:0xf bound_ctrl:1
	global_store_short v[2:3], v62, off
	v_lshl_add_u64 v[2:3], v[2:3], 0, s[84:85]
	v_add_f32_dpp v12, v12, v12 row_ror:8 row_mask:0xf bank_mask:0xf bound_ctrl:1
	v_pk_fma_f32 v[6:7], v[114:115], v[12:13], v[48:49] op_sel_hi:[1,0,1] neg_lo:[1,0,0] neg_hi:[1,0,0]
	v_pk_fma_f32 v[8:9], v[116:117], v[12:13], v[50:51] op_sel_hi:[1,0,1] neg_lo:[1,0,0] neg_hi:[1,0,0]
	v_pk_mul_f32 v[6:7], v[6:7], v[106:107]
	v_pk_mul_f32 v[8:9], v[8:9], v[108:109]
	ds_read_b128 v[36:39], v10 offset:50432
	ds_read_b128 v[44:47], v10 offset:50944
	ds_read_b128 v[40:43], v10 offset:50688
	s_waitcnt lgkmcnt(3)
	v_fma_mix_f32 v12, v6, v20, v180 op_sel_hi:[0,1,0]
	v_fma_mix_f32 v12, v7, v20, v12 op_sel:[0,1,0] op_sel_hi:[0,1,0]
	v_fma_mix_f32 v12, v8, v21, v12 op_sel_hi:[0,1,0]
	v_fma_mix_f32 v12, v9, v21, v12 op_sel:[0,1,0] op_sel_hi:[0,1,0]
	v_fma_mix_f32 v61, v6, v112, v180 op_sel_hi:[0,1,0]
	v_fma_mix_f32 v61, v7, v112, v61 op_sel:[0,1,0] op_sel_hi:[0,1,0]
	v_add_f32_dpp v12, v12, v12 row_ror:1 row_mask:0xf bank_mask:0xf bound_ctrl:1
	v_fma_mix_f32 v61, v8, v113, v61 op_sel_hi:[0,1,0]
	v_fma_mix_f32 v61, v9, v113, v61 op_sel:[0,1,0] op_sel_hi:[0,1,0]
	v_add_f32_dpp v12, v12, v12 row_ror:2 row_mask:0xf bank_mask:0xf bound_ctrl:1
	v_pk_fma_f32 v[48:49], v[28:29], v[66:67], v[6:7] op_sel_hi:[1,0,1]
	v_pk_fma_f32 v[50:51], v[30:31], v[66:67], v[8:9] op_sel_hi:[1,0,1]
	v_add_f32_dpp v12, v12, v12 row_ror:4 row_mask:0xf bank_mask:0xf bound_ctrl:1
	s_nop 1
	v_add_f32_dpp v12, v12, v12 row_ror:8 row_mask:0xf bank_mask:0xf bound_ctrl:1
	v_pk_fma_f32 v[6:7], v[24:25], v[12:13], v[48:49] op_sel_hi:[1,0,1] neg_lo:[1,0,0] neg_hi:[1,0,0]
	v_pk_fma_f32 v[8:9], v[26:27], v[12:13], v[50:51] op_sel_hi:[1,0,1] neg_lo:[1,0,0] neg_hi:[1,0,0]
	ds_read_b128 v[88:91], v10 offset:51456
	ds_read_b128 v[96:99], v10 offset:51968
	ds_read_b128 v[92:95], v10 offset:51712
	s_waitcnt lgkmcnt(3)
	v_fma_mix_f32 v12, v6, v36, v180 op_sel_hi:[0,1,0]
	v_fma_mix_f32 v12, v7, v36, v12 op_sel:[0,1,0] op_sel_hi:[0,1,0]
	v_fma_mix_f32 v12, v8, v37, v12 op_sel_hi:[0,1,0]
	v_fma_mix_f32 v12, v9, v37, v12 op_sel:[0,1,0] op_sel_hi:[0,1,0]
	v_fma_mix_f32 v122, v6, v22, v180 op_sel_hi:[0,1,0]
	v_fma_mix_f32 v122, v7, v22, v122 op_sel:[0,1,0] op_sel_hi:[0,1,0]
	v_add_f32_dpp v12, v12, v12 row_ror:1 row_mask:0xf bank_mask:0xf bound_ctrl:1
	v_fma_mix_f32 v122, v8, v23, v122 op_sel_hi:[0,1,0]
	v_fma_mix_f32 v122, v9, v23, v122 op_sel:[0,1,0] op_sel_hi:[0,1,0]
	v_add_f32_dpp v12, v12, v12 row_ror:2 row_mask:0xf bank_mask:0xf bound_ctrl:1
	v_pk_fma_f32 v[48:49], v[44:45], v[66:67], v[6:7] op_sel:[0,1,0]
	v_pk_fma_f32 v[50:51], v[46:47], v[66:67], v[8:9] op_sel:[0,1,0]
	v_add_f32_dpp v12, v12, v12 row_ror:4 row_mask:0xf bank_mask:0xf bound_ctrl:1
	v_add_f32_dpp v83, v83, v83 row_ror:8 row_mask:0xf bank_mask:0xc
	v_add_f32_dpp v83, v52, v52 row_ror:8 row_mask:0xf bank_mask:0x3
	v_add_f32_dpp v100, v100, v100 row_ror:8 row_mask:0xf bank_mask:0xc
	v_add_f32_dpp v12, v12, v12 row_ror:8 row_mask:0xf bank_mask:0xf bound_ctrl:1
	v_pk_fma_f32 v[6:7], v[40:41], v[12:13], v[48:49] op_sel_hi:[1,0,1] neg_lo:[1,0,0] neg_hi:[1,0,0]
	v_pk_fma_f32 v[8:9], v[42:43], v[12:13], v[50:51] op_sel_hi:[1,0,1] neg_lo:[1,0,0] neg_hi:[1,0,0]
	ds_read_b128 v[110:113], v10 offset:52480
	ds_read_b128 v[106:109], v10 offset:52224
	ds_read_b128 v[118:121], v10 offset:52992
	ds_read_b128 v[114:117], v10 offset:52736
	ds_read_b128 v[70:73], v11 offset:3328
	s_waitcnt lgkmcnt(5)
	v_fma_mix_f32 v12, v6, v88, v180 op_sel_hi:[0,1,0]
	v_fma_mix_f32 v12, v7, v88, v12 op_sel:[0,1,0] op_sel_hi:[0,1,0]
	v_fma_mix_f32 v12, v8, v89, v12 op_sel_hi:[0,1,0]
	v_fma_mix_f32 v12, v9, v89, v12 op_sel:[0,1,0] op_sel_hi:[0,1,0]
	v_fma_mix_f32 v123, v6, v38, v180 op_sel_hi:[0,1,0]
	v_fma_mix_f32 v123, v7, v38, v123 op_sel:[0,1,0] op_sel_hi:[0,1,0]
	v_add_f32_dpp v12, v12, v12 row_ror:1 row_mask:0xf bank_mask:0xf bound_ctrl:1
	v_fma_mix_f32 v123, v8, v39, v123 op_sel_hi:[0,1,0]
	v_fma_mix_f32 v123, v9, v39, v123 op_sel:[0,1,0] op_sel_hi:[0,1,0]
	v_add_f32_dpp v12, v12, v12 row_ror:2 row_mask:0xf bank_mask:0xf bound_ctrl:1
	v_pk_fma_f32 v[48:49], v[96:97], v[68:69], v[6:7] op_sel_hi:[1,0,1]
	v_pk_fma_f32 v[50:51], v[98:99], v[68:69], v[8:9] op_sel_hi:[1,0,1]
	v_add_f32_dpp v12, v12, v12 row_ror:4 row_mask:0xf bank_mask:0xf bound_ctrl:1
	v_add_f32_dpp v100, v53, v53 row_ror:8 row_mask:0xf bank_mask:0x3
	v_add_f32_dpp v101, v101, v101 row_ror:8 row_mask:0xf bank_mask:0xc
	v_add_f32_dpp v101, v54, v54 row_ror:8 row_mask:0xf bank_mask:0x3
	v_add_f32_dpp v12, v12, v12 row_ror:8 row_mask:0xf bank_mask:0xf bound_ctrl:1
	v_pk_fma_f32 v[6:7], v[92:93], v[12:13], v[48:49] op_sel_hi:[1,0,1] neg_lo:[1,0,0] neg_hi:[1,0,0]
	v_pk_fma_f32 v[8:9], v[94:95], v[12:13], v[50:51] op_sel_hi:[1,0,1] neg_lo:[1,0,0] neg_hi:[1,0,0]
	ds_read_b128 v[20:23], v10 offset:53504
	ds_read_b128 v[28:31], v10 offset:54016
	ds_read_b128 v[24:27], v10 offset:53760
	s_waitcnt lgkmcnt(4)
	v_fma_mix_f32 v12, v6, v110, v180 op_sel_hi:[0,1,0]
	v_fma_mix_f32 v12, v7, v110, v12 op_sel:[0,1,0] op_sel_hi:[0,1,0]
	v_fma_mix_f32 v12, v8, v111, v12 op_sel_hi:[0,1,0]
	v_fma_mix_f32 v12, v9, v111, v12 op_sel:[0,1,0] op_sel_hi:[0,1,0]
	v_fma_mix_f32 v124, v6, v90, v180 op_sel_hi:[0,1,0]
	v_fma_mix_f32 v124, v7, v90, v124 op_sel:[0,1,0] op_sel_hi:[0,1,0]
	v_add_f32_dpp v12, v12, v12 row_ror:1 row_mask:0xf bank_mask:0xf bound_ctrl:1
	v_fma_mix_f32 v124, v8, v91, v124 op_sel_hi:[0,1,0]
	v_fma_mix_f32 v124, v9, v91, v124 op_sel:[0,1,0] op_sel_hi:[0,1,0]
	v_add_f32_dpp v12, v12, v12 row_ror:2 row_mask:0xf bank_mask:0xf bound_ctrl:1
	v_pk_fma_f32 v[48:49], v[118:119], v[68:69], v[6:7] op_sel:[0,1,0]
	v_pk_fma_f32 v[50:51], v[120:121], v[68:69], v[8:9] op_sel:[0,1,0]
	v_add_f32_dpp v12, v12, v12 row_ror:4 row_mask:0xf bank_mask:0xf bound_ctrl:1
	v_add_f32_dpp v102, v102, v102 row_ror:8 row_mask:0xf bank_mask:0xc
	v_add_f32_dpp v102, v55, v55 row_ror:8 row_mask:0xf bank_mask:0x3
	v_add_f32_dpp v103, v103, v103 row_ror:8 row_mask:0xf bank_mask:0xc
	v_add_f32_dpp v12, v12, v12 row_ror:8 row_mask:0xf bank_mask:0xf bound_ctrl:1
	v_pk_fma_f32 v[6:7], v[114:115], v[12:13], v[48:49] op_sel_hi:[1,0,1] neg_lo:[1,0,0] neg_hi:[1,0,0]
	v_pk_fma_f32 v[8:9], v[116:117], v[12:13], v[50:51] op_sel_hi:[1,0,1] neg_lo:[1,0,0] neg_hi:[1,0,0]
	v_pk_mul_f32 v[6:7], v[6:7], v[106:107]
	v_pk_mul_f32 v[8:9], v[8:9], v[108:109]
	ds_read_b128 v[36:39], v10 offset:54528
	ds_read_b128 v[44:47], v10 offset:55040
	ds_read_b128 v[40:43], v10 offset:54784
	s_waitcnt lgkmcnt(3)
	v_fma_mix_f32 v12, v6, v20, v180 op_sel_hi:[0,1,0]
	v_fma_mix_f32 v12, v7, v20, v12 op_sel:[0,1,0] op_sel_hi:[0,1,0]
	v_fma_mix_f32 v12, v8, v21, v12 op_sel_hi:[0,1,0]
	v_fma_mix_f32 v12, v9, v21, v12 op_sel:[0,1,0] op_sel_hi:[0,1,0]
	v_fma_mix_f32 v125, v6, v112, v180 op_sel_hi:[0,1,0]
	v_fma_mix_f32 v125, v7, v112, v125 op_sel:[0,1,0] op_sel_hi:[0,1,0]
	v_add_f32_dpp v12, v12, v12 row_ror:1 row_mask:0xf bank_mask:0xf bound_ctrl:1
	v_fma_mix_f32 v125, v8, v113, v125 op_sel_hi:[0,1,0]
	v_fma_mix_f32 v125, v9, v113, v125 op_sel:[0,1,0] op_sel_hi:[0,1,0]
	v_add_f32_dpp v12, v12, v12 row_ror:2 row_mask:0xf bank_mask:0xf bound_ctrl:1
	v_pk_fma_f32 v[48:49], v[28:29], v[70:71], v[6:7] op_sel_hi:[1,0,1]
	v_pk_fma_f32 v[50:51], v[30:31], v[70:71], v[8:9] op_sel_hi:[1,0,1]
	v_add_f32_dpp v12, v12, v12 row_ror:4 row_mask:0xf bank_mask:0xf bound_ctrl:1
	v_add_f32_dpp v103, v56, v56 row_ror:8 row_mask:0xf bank_mask:0x3
	v_add_f32_dpp v104, v104, v104 row_ror:8 row_mask:0xf bank_mask:0xc
	v_add_f32_dpp v104, v57, v57 row_ror:8 row_mask:0xf bank_mask:0x3
	v_add_f32_dpp v12, v12, v12 row_ror:8 row_mask:0xf bank_mask:0xf bound_ctrl:1
	v_pk_fma_f32 v[6:7], v[24:25], v[12:13], v[48:49] op_sel_hi:[1,0,1] neg_lo:[1,0,0] neg_hi:[1,0,0]
	v_pk_fma_f32 v[8:9], v[26:27], v[12:13], v[50:51] op_sel_hi:[1,0,1] neg_lo:[1,0,0] neg_hi:[1,0,0]
	ds_read_b128 v[88:91], v10 offset:55552
	ds_read_b128 v[96:99], v10 offset:56064
	ds_read_b128 v[92:95], v10 offset:55808
	s_waitcnt lgkmcnt(3)
	v_fma_mix_f32 v12, v6, v36, v180 op_sel_hi:[0,1,0]
	v_fma_mix_f32 v12, v7, v36, v12 op_sel:[0,1,0] op_sel_hi:[0,1,0]
	v_fma_mix_f32 v12, v8, v37, v12 op_sel_hi:[0,1,0]
	v_fma_mix_f32 v12, v9, v37, v12 op_sel:[0,1,0] op_sel_hi:[0,1,0]
	v_fma_mix_f32 v126, v6, v22, v180 op_sel_hi:[0,1,0]
	v_fma_mix_f32 v126, v7, v22, v126 op_sel:[0,1,0] op_sel_hi:[0,1,0]
	v_add_f32_dpp v12, v12, v12 row_ror:1 row_mask:0xf bank_mask:0xf bound_ctrl:1
	v_fma_mix_f32 v126, v8, v23, v126 op_sel_hi:[0,1,0]
	v_fma_mix_f32 v126, v9, v23, v126 op_sel:[0,1,0] op_sel_hi:[0,1,0]
	v_add_f32_dpp v12, v12, v12 row_ror:2 row_mask:0xf bank_mask:0xf bound_ctrl:1
	v_pk_fma_f32 v[48:49], v[44:45], v[70:71], v[6:7] op_sel:[0,1,0]
	v_pk_fma_f32 v[50:51], v[46:47], v[70:71], v[8:9] op_sel:[0,1,0]
	v_add_f32_dpp v12, v12, v12 row_ror:4 row_mask:0xf bank_mask:0xf bound_ctrl:1
	v_add_f32_dpp v105, v105, v105 row_ror:8 row_mask:0xf bank_mask:0xc
	v_add_f32_dpp v105, v81, v81 row_ror:8 row_mask:0xf bank_mask:0x3
	v_add_f32_dpp v12, v12, v12 row_ror:8 row_mask:0xf bank_mask:0xf bound_ctrl:1
	v_pk_fma_f32 v[6:7], v[40:41], v[12:13], v[48:49] op_sel_hi:[1,0,1] neg_lo:[1,0,0] neg_hi:[1,0,0]
	v_pk_fma_f32 v[8:9], v[42:43], v[12:13], v[50:51] op_sel_hi:[1,0,1] neg_lo:[1,0,0] neg_hi:[1,0,0]
	ds_read_b128 v[110:113], v10 offset:56576
	ds_read_b128 v[106:109], v10 offset:56320
	ds_read_b128 v[118:121], v10 offset:57088
	ds_read_b128 v[114:117], v10 offset:56832
	ds_read_b128 v[66:69], v11 offset:3584
	s_waitcnt lgkmcnt(5)
	v_fma_mix_f32 v12, v6, v88, v180 op_sel_hi:[0,1,0]
	v_fma_mix_f32 v12, v7, v88, v12 op_sel:[0,1,0] op_sel_hi:[0,1,0]
	v_fma_mix_f32 v12, v8, v89, v12 op_sel_hi:[0,1,0]
	v_fma_mix_f32 v12, v9, v89, v12 op_sel:[0,1,0] op_sel_hi:[0,1,0]
	v_fma_mix_f32 v127, v6, v38, v180 op_sel_hi:[0,1,0]
	v_fma_mix_f32 v127, v7, v38, v127 op_sel:[0,1,0] op_sel_hi:[0,1,0]
	v_add_f32_dpp v12, v12, v12 row_ror:1 row_mask:0xf bank_mask:0xf bound_ctrl:1
	v_fma_mix_f32 v127, v8, v39, v127 op_sel_hi:[0,1,0]
	v_fma_mix_f32 v127, v9, v39, v127 op_sel:[0,1,0] op_sel_hi:[0,1,0]
	v_add_f32_dpp v12, v12, v12 row_ror:2 row_mask:0xf bank_mask:0xf bound_ctrl:1
	v_pk_fma_f32 v[48:49], v[96:97], v[72:73], v[6:7] op_sel_hi:[1,0,1]
	v_pk_fma_f32 v[50:51], v[98:99], v[72:73], v[8:9] op_sel_hi:[1,0,1]
	v_add_f32_dpp v12, v12, v12 row_ror:4 row_mask:0xf bank_mask:0xf bound_ctrl:1
	v_add_f32_dpp v61, v61, v61 row_ror:8 row_mask:0xf bank_mask:0xc
	v_add_f32_dpp v61, v82, v82 row_ror:8 row_mask:0xf bank_mask:0x3
	v_add_f32_dpp v12, v12, v12 row_ror:8 row_mask:0xf bank_mask:0xf bound_ctrl:1
	v_pk_fma_f32 v[6:7], v[92:93], v[12:13], v[48:49] op_sel_hi:[1,0,1] neg_lo:[1,0,0] neg_hi:[1,0,0]
	v_pk_fma_f32 v[8:9], v[94:95], v[12:13], v[50:51] op_sel_hi:[1,0,1] neg_lo:[1,0,0] neg_hi:[1,0,0]
	ds_read_b128 v[20:23], v10 offset:57600
	ds_read_b128 v[28:31], v10 offset:58112
	ds_read_b128 v[24:27], v10 offset:57856
	s_waitcnt lgkmcnt(4)
	v_fma_mix_f32 v12, v6, v110, v180 op_sel_hi:[0,1,0]
	v_fma_mix_f32 v12, v7, v110, v12 op_sel:[0,1,0] op_sel_hi:[0,1,0]
	v_fma_mix_f32 v12, v8, v111, v12 op_sel_hi:[0,1,0]
	v_fma_mix_f32 v12, v9, v111, v12 op_sel:[0,1,0] op_sel_hi:[0,1,0]
	v_fma_mix_f32 v128, v6, v90, v180 op_sel_hi:[0,1,0]
	v_fma_mix_f32 v128, v7, v90, v128 op_sel:[0,1,0] op_sel_hi:[0,1,0]
	v_add_f32_dpp v12, v12, v12 row_ror:1 row_mask:0xf bank_mask:0xf bound_ctrl:1
	v_fma_mix_f32 v128, v8, v91, v128 op_sel_hi:[0,1,0]
	v_fma_mix_f32 v128, v9, v91, v128 op_sel:[0,1,0] op_sel_hi:[0,1,0]
	v_add_f32_dpp v12, v12, v12 row_ror:2 row_mask:0xf bank_mask:0xf bound_ctrl:1
	v_pk_fma_f32 v[48:49], v[118:119], v[72:73], v[6:7] op_sel:[0,1,0]
	v_pk_fma_f32 v[50:51], v[120:121], v[72:73], v[8:9] op_sel:[0,1,0]
	v_add_f32_dpp v12, v12, v12 row_ror:4 row_mask:0xf bank_mask:0xf bound_ctrl:1
	v_add_f32_dpp v103, v103, v103 row_ror:4 row_mask:0xf bank_mask:0xa
	v_add_f32_dpp v103, v83, v83 row_ror:12 row_mask:0xf bank_mask:0x5
	v_add_f32_dpp v104, v104, v104 row_ror:4 row_mask:0xf bank_mask:0xa
	v_add_f32_dpp v12, v12, v12 row_ror:8 row_mask:0xf bank_mask:0xf bound_ctrl:1
	v_pk_fma_f32 v[6:7], v[114:115], v[12:13], v[48:49] op_sel_hi:[1,0,1] neg_lo:[1,0,0] neg_hi:[1,0,0]
	v_pk_fma_f32 v[8:9], v[116:117], v[12:13], v[50:51] op_sel_hi:[1,0,1] neg_lo:[1,0,0] neg_hi:[1,0,0]
	v_pk_mul_f32 v[6:7], v[6:7], v[106:107]
	v_pk_mul_f32 v[8:9], v[8:9], v[108:109]
	ds_read_b128 v[36:39], v10 offset:58624
	ds_read_b128 v[44:47], v10 offset:59136
	ds_read_b128 v[40:43], v10 offset:58880
	s_waitcnt lgkmcnt(3)
	v_fma_mix_f32 v12, v6, v20, v180 op_sel_hi:[0,1,0]
	v_fma_mix_f32 v12, v7, v20, v12 op_sel:[0,1,0] op_sel_hi:[0,1,0]
	v_fma_mix_f32 v12, v8, v21, v12 op_sel_hi:[0,1,0]
	v_fma_mix_f32 v12, v9, v21, v12 op_sel:[0,1,0] op_sel_hi:[0,1,0]
	v_fma_mix_f32 v129, v6, v112, v180 op_sel_hi:[0,1,0]
	v_fma_mix_f32 v129, v7, v112, v129 op_sel:[0,1,0] op_sel_hi:[0,1,0]
	v_add_f32_dpp v12, v12, v12 row_ror:1 row_mask:0xf bank_mask:0xf bound_ctrl:1
	v_fma_mix_f32 v129, v8, v113, v129 op_sel_hi:[0,1,0]
	v_fma_mix_f32 v129, v9, v113, v129 op_sel:[0,1,0] op_sel_hi:[0,1,0]
	v_add_f32_dpp v12, v12, v12 row_ror:2 row_mask:0xf bank_mask:0xf bound_ctrl:1
	v_pk_fma_f32 v[48:49], v[28:29], v[66:67], v[6:7] op_sel_hi:[1,0,1]
	v_pk_fma_f32 v[50:51], v[30:31], v[66:67], v[8:9] op_sel_hi:[1,0,1]
	v_add_f32_dpp v12, v12, v12 row_ror:4 row_mask:0xf bank_mask:0xf bound_ctrl:1
	v_add_f32_dpp v104, v100, v100 row_ror:12 row_mask:0xf bank_mask:0x5
	v_add_f32_dpp v105, v105, v105 row_ror:4 row_mask:0xf bank_mask:0xa
	v_add_f32_dpp v105, v101, v101 row_ror:12 row_mask:0xf bank_mask:0x5
	v_add_f32_dpp v12, v12, v12 row_ror:8 row_mask:0xf bank_mask:0xf bound_ctrl:1
	v_pk_fma_f32 v[6:7], v[24:25], v[12:13], v[48:49] op_sel_hi:[1,0,1] neg_lo:[1,0,0] neg_hi:[1,0,0]
	v_pk_fma_f32 v[8:9], v[26:27], v[12:13], v[50:51] op_sel_hi:[1,0,1] neg_lo:[1,0,0] neg_hi:[1,0,0]
	ds_read_b128 v[88:91], v10 offset:59648
	ds_read_b128 v[96:99], v10 offset:60160
	ds_read_b128 v[92:95], v10 offset:59904
	s_waitcnt lgkmcnt(3)
	v_fma_mix_f32 v12, v6, v36, v180 op_sel_hi:[0,1,0]
	v_fma_mix_f32 v12, v7, v36, v12 op_sel:[0,1,0] op_sel_hi:[0,1,0]
	v_fma_mix_f32 v12, v8, v37, v12 op_sel_hi:[0,1,0]
	v_fma_mix_f32 v12, v9, v37, v12 op_sel:[0,1,0] op_sel_hi:[0,1,0]
	v_fma_mix_f32 v130, v6, v22, v180 op_sel_hi:[0,1,0]
	v_fma_mix_f32 v130, v7, v22, v130 op_sel:[0,1,0] op_sel_hi:[0,1,0]
	v_add_f32_dpp v12, v12, v12 row_ror:1 row_mask:0xf bank_mask:0xf bound_ctrl:1
	v_fma_mix_f32 v130, v8, v23, v130 op_sel_hi:[0,1,0]
	v_fma_mix_f32 v130, v9, v23, v130 op_sel:[0,1,0] op_sel_hi:[0,1,0]
	v_add_f32_dpp v12, v12, v12 row_ror:2 row_mask:0xf bank_mask:0xf bound_ctrl:1
	v_pk_fma_f32 v[48:49], v[44:45], v[66:67], v[6:7] op_sel:[0,1,0]
	v_pk_fma_f32 v[50:51], v[46:47], v[66:67], v[8:9] op_sel:[0,1,0]
	v_add_f32_dpp v12, v12, v12 row_ror:4 row_mask:0xf bank_mask:0xf bound_ctrl:1
	v_add_f32_dpp v61, v61, v61 row_ror:4 row_mask:0xf bank_mask:0xa
	v_add_f32_dpp v61, v102, v102 row_ror:12 row_mask:0xf bank_mask:0x5
	v_add_f32_dpp v12, v12, v12 row_ror:8 row_mask:0xf bank_mask:0xf bound_ctrl:1
	v_pk_fma_f32 v[6:7], v[40:41], v[12:13], v[48:49] op_sel_hi:[1,0,1] neg_lo:[1,0,0] neg_hi:[1,0,0]
	v_pk_fma_f32 v[8:9], v[42:43], v[12:13], v[50:51] op_sel_hi:[1,0,1] neg_lo:[1,0,0] neg_hi:[1,0,0]
	ds_read_b128 v[110:113], v10 offset:60672
	ds_read_b128 v[106:109], v10 offset:60416
	ds_read_b128 v[118:121], v10 offset:61184
	ds_read_b128 v[114:117], v10 offset:60928
	ds_read_b128 v[70:73], v11 offset:3840
	s_waitcnt lgkmcnt(5)
	v_fma_mix_f32 v12, v6, v88, v180 op_sel_hi:[0,1,0]
	v_fma_mix_f32 v12, v7, v88, v12 op_sel:[0,1,0] op_sel_hi:[0,1,0]
	v_fma_mix_f32 v12, v8, v89, v12 op_sel_hi:[0,1,0]
	v_fma_mix_f32 v12, v9, v89, v12 op_sel:[0,1,0] op_sel_hi:[0,1,0]
	v_fma_mix_f32 v131, v6, v38, v180 op_sel_hi:[0,1,0]
	v_fma_mix_f32 v131, v7, v38, v131 op_sel:[0,1,0] op_sel_hi:[0,1,0]
	v_add_f32_dpp v12, v12, v12 row_ror:1 row_mask:0xf bank_mask:0xf bound_ctrl:1
	v_fma_mix_f32 v131, v8, v39, v131 op_sel_hi:[0,1,0]
	v_fma_mix_f32 v131, v9, v39, v131 op_sel:[0,1,0] op_sel_hi:[0,1,0]
	v_add_f32_dpp v12, v12, v12 row_ror:2 row_mask:0xf bank_mask:0xf bound_ctrl:1
	v_pk_fma_f32 v[48:49], v[96:97], v[68:69], v[6:7] op_sel_hi:[1,0,1]
	v_pk_fma_f32 v[50:51], v[98:99], v[68:69], v[8:9] op_sel_hi:[1,0,1]
	v_add_f32_dpp v12, v12, v12 row_ror:4 row_mask:0xf bank_mask:0xf bound_ctrl:1
	v_cndmask_b32_e64 v62, v105, v103, s[38:39]
	v_cndmask_b32_e64 v63, v103, v105, s[38:39]
	v_add_f32_dpp v12, v12, v12 row_ror:8 row_mask:0xf bank_mask:0xf bound_ctrl:1
	v_pk_fma_f32 v[6:7], v[92:93], v[12:13], v[48:49] op_sel_hi:[1,0,1] neg_lo:[1,0,0] neg_hi:[1,0,0]
	v_pk_fma_f32 v[8:9], v[94:95], v[12:13], v[50:51] op_sel_hi:[1,0,1] neg_lo:[1,0,0] neg_hi:[1,0,0]
	ds_read_b128 v[20:23], v10 offset:61696
	ds_read_b128 v[28:31], v10 offset:62208
	ds_read_b128 v[24:27], v10 offset:61952
	s_waitcnt lgkmcnt(4)
	v_fma_mix_f32 v12, v6, v110, v180 op_sel_hi:[0,1,0]
	v_fma_mix_f32 v12, v7, v110, v12 op_sel:[0,1,0] op_sel_hi:[0,1,0]
	v_fma_mix_f32 v12, v8, v111, v12 op_sel_hi:[0,1,0]
	v_fma_mix_f32 v12, v9, v111, v12 op_sel:[0,1,0] op_sel_hi:[0,1,0]
	v_fma_mix_f32 v132, v6, v90, v180 op_sel_hi:[0,1,0]
	v_fma_mix_f32 v132, v7, v90, v132 op_sel:[0,1,0] op_sel_hi:[0,1,0]
	v_add_f32_dpp v12, v12, v12 row_ror:1 row_mask:0xf bank_mask:0xf bound_ctrl:1
	v_fma_mix_f32 v132, v8, v91, v132 op_sel_hi:[0,1,0]
	v_fma_mix_f32 v132, v9, v91, v132 op_sel:[0,1,0] op_sel_hi:[0,1,0]
	v_add_f32_dpp v12, v12, v12 row_ror:2 row_mask:0xf bank_mask:0xf bound_ctrl:1
	v_pk_fma_f32 v[48:49], v[118:119], v[68:69], v[6:7] op_sel:[0,1,0]
	v_pk_fma_f32 v[50:51], v[120:121], v[68:69], v[8:9] op_sel:[0,1,0]
	v_add_f32_dpp v12, v12, v12 row_ror:4 row_mask:0xf bank_mask:0xf bound_ctrl:1
	v_cndmask_b32_e64 v64, v61, v104, s[38:39]
	v_cndmask_b32_e64 v65, v104, v61, s[38:39]
	v_add_f32_dpp v12, v12, v12 row_ror:8 row_mask:0xf bank_mask:0xf bound_ctrl:1
	v_pk_fma_f32 v[6:7], v[114:115], v[12:13], v[48:49] op_sel_hi:[1,0,1] neg_lo:[1,0,0] neg_hi:[1,0,0]
	v_pk_fma_f32 v[8:9], v[116:117], v[12:13], v[50:51] op_sel_hi:[1,0,1] neg_lo:[1,0,0] neg_hi:[1,0,0]
	v_pk_mul_f32 v[6:7], v[6:7], v[106:107]
	v_pk_mul_f32 v[8:9], v[8:9], v[108:109]
	ds_read_b128 v[36:39], v10 offset:62720
	ds_read_b128 v[44:47], v10 offset:63232
	ds_read_b128 v[40:43], v10 offset:62976
	s_waitcnt lgkmcnt(3)
	v_fma_mix_f32 v12, v6, v20, v180 op_sel_hi:[0,1,0]
	v_fma_mix_f32 v12, v7, v20, v12 op_sel:[0,1,0] op_sel_hi:[0,1,0]
	v_fma_mix_f32 v12, v8, v21, v12 op_sel_hi:[0,1,0]
	v_fma_mix_f32 v12, v9, v21, v12 op_sel:[0,1,0] op_sel_hi:[0,1,0]
	v_fma_mix_f32 v133, v6, v112, v180 op_sel_hi:[0,1,0]
	v_fma_mix_f32 v133, v7, v112, v133 op_sel:[0,1,0] op_sel_hi:[0,1,0]
	v_add_f32_dpp v12, v12, v12 row_ror:1 row_mask:0xf bank_mask:0xf bound_ctrl:1
	v_fma_mix_f32 v133, v8, v113, v133 op_sel_hi:[0,1,0]
	v_fma_mix_f32 v133, v9, v113, v133 op_sel:[0,1,0] op_sel_hi:[0,1,0]
	v_add_f32_dpp v12, v12, v12 row_ror:2 row_mask:0xf bank_mask:0xf bound_ctrl:1
	v_pk_fma_f32 v[48:49], v[28:29], v[70:71], v[6:7] op_sel_hi:[1,0,1]
	v_pk_fma_f32 v[50:51], v[30:31], v[70:71], v[8:9] op_sel_hi:[1,0,1]
	v_add_f32_dpp v12, v12, v12 row_ror:4 row_mask:0xf bank_mask:0xf bound_ctrl:1
	v_add_f32_dpp v62, v63, v62 quad_perm:[2,3,0,1] row_mask:0xf bank_mask:0xf bound_ctrl:1
	v_add_f32_dpp v63, v65, v64 quad_perm:[2,3,0,1] row_mask:0xf bank_mask:0xf bound_ctrl:1
	v_add_f32_dpp v12, v12, v12 row_ror:8 row_mask:0xf bank_mask:0xf bound_ctrl:1
	v_pk_fma_f32 v[6:7], v[24:25], v[12:13], v[48:49] op_sel_hi:[1,0,1] neg_lo:[1,0,0] neg_hi:[1,0,0]
	v_pk_fma_f32 v[8:9], v[26:27], v[12:13], v[50:51] op_sel_hi:[1,0,1] neg_lo:[1,0,0] neg_hi:[1,0,0]
	ds_read_b128 v[88:91], v10 offset:63744
	ds_read_b128 v[96:99], v10 offset:64256
	ds_read_b128 v[92:95], v10 offset:64000
	s_waitcnt lgkmcnt(3)
	v_fma_mix_f32 v12, v6, v36, v180 op_sel_hi:[0,1,0]
	v_fma_mix_f32 v12, v7, v36, v12 op_sel:[0,1,0] op_sel_hi:[0,1,0]
	v_fma_mix_f32 v12, v8, v37, v12 op_sel_hi:[0,1,0]
	v_fma_mix_f32 v12, v9, v37, v12 op_sel:[0,1,0] op_sel_hi:[0,1,0]
	v_fma_mix_f32 v134, v6, v22, v180 op_sel_hi:[0,1,0]
	v_fma_mix_f32 v134, v7, v22, v134 op_sel:[0,1,0] op_sel_hi:[0,1,0]
	v_add_f32_dpp v12, v12, v12 row_ror:1 row_mask:0xf bank_mask:0xf bound_ctrl:1
	v_fma_mix_f32 v134, v8, v23, v134 op_sel_hi:[0,1,0]
	v_fma_mix_f32 v134, v9, v23, v134 op_sel:[0,1,0] op_sel_hi:[0,1,0]
	v_add_f32_dpp v12, v12, v12 row_ror:2 row_mask:0xf bank_mask:0xf bound_ctrl:1
	v_pk_fma_f32 v[48:49], v[44:45], v[70:71], v[6:7] op_sel:[0,1,0]
	v_pk_fma_f32 v[50:51], v[46:47], v[70:71], v[8:9] op_sel:[0,1,0]
	v_add_f32_dpp v12, v12, v12 row_ror:4 row_mask:0xf bank_mask:0xf bound_ctrl:1
	v_cndmask_b32_e64 v65, v63, v62, s[40:41]
	v_cndmask_b32_e64 v62, v62, v63, s[40:41]
	v_add_f32_dpp v12, v12, v12 row_ror:8 row_mask:0xf bank_mask:0xf bound_ctrl:1
	v_pk_fma_f32 v[6:7], v[40:41], v[12:13], v[48:49] op_sel_hi:[1,0,1] neg_lo:[1,0,0] neg_hi:[1,0,0]
	v_pk_fma_f32 v[8:9], v[42:43], v[12:13], v[50:51] op_sel_hi:[1,0,1] neg_lo:[1,0,0] neg_hi:[1,0,0]
	ds_read_b128 v[110:113], v10 offset:64768
	ds_read_b128 v[106:109], v10 offset:64512
	ds_read_b128 v[118:121], v10 offset:65280
	ds_read_b128 v[114:117], v10 offset:65024
	s_waitcnt lgkmcnt(4)
	v_fma_mix_f32 v12, v6, v88, v180 op_sel_hi:[0,1,0]
	v_fma_mix_f32 v12, v7, v88, v12 op_sel:[0,1,0] op_sel_hi:[0,1,0]
	v_fma_mix_f32 v12, v8, v89, v12 op_sel_hi:[0,1,0]
	v_fma_mix_f32 v12, v9, v89, v12 op_sel:[0,1,0] op_sel_hi:[0,1,0]
	v_fma_mix_f32 v135, v6, v38, v180 op_sel_hi:[0,1,0]
	v_fma_mix_f32 v135, v7, v38, v135 op_sel:[0,1,0] op_sel_hi:[0,1,0]
	v_add_f32_dpp v12, v12, v12 row_ror:1 row_mask:0xf bank_mask:0xf bound_ctrl:1
	v_fma_mix_f32 v135, v8, v39, v135 op_sel_hi:[0,1,0]
	v_fma_mix_f32 v135, v9, v39, v135 op_sel:[0,1,0] op_sel_hi:[0,1,0]
	v_add_f32_dpp v12, v12, v12 row_ror:2 row_mask:0xf bank_mask:0xf bound_ctrl:1
	v_pk_fma_f32 v[48:49], v[96:97], v[72:73], v[6:7] op_sel_hi:[1,0,1]
	v_pk_fma_f32 v[50:51], v[98:99], v[72:73], v[8:9] op_sel_hi:[1,0,1]
	v_add_f32_dpp v12, v12, v12 row_ror:4 row_mask:0xf bank_mask:0xf bound_ctrl:1
	v_add_f32_dpp v62, v62, v65 quad_perm:[1,0,3,2] row_mask:0xf bank_mask:0xf bound_ctrl:1
	v_cvt_pk_bf16_f32 v62, v62, v62
	v_add_f32_dpp v12, v12, v12 row_ror:8 row_mask:0xf bank_mask:0xf bound_ctrl:1
	v_pk_fma_f32 v[6:7], v[92:93], v[12:13], v[48:49] op_sel_hi:[1,0,1] neg_lo:[1,0,0] neg_hi:[1,0,0]
	v_pk_fma_f32 v[8:9], v[94:95], v[12:13], v[50:51] op_sel_hi:[1,0,1] neg_lo:[1,0,0] neg_hi:[1,0,0]
	s_waitcnt lgkmcnt(0)
	s_barrier
	v_xor_b32_e32 v10, 0x10000, v10
	v_xor_b32_e32 v11, 0x1000, v11
	ds_read_b128 v[66:69], v11 offset:0
	ds_read_b128 v[20:23], v10 offset:256
	ds_read_b128 v[28:31], v10 offset:768
	ds_read_b128 v[24:27], v10 offset:512
	ds_read_b128 v[36:39], v10 offset:1280
	ds_read_b128 v[44:47], v10 offset:1792
	ds_read_b128 v[40:43], v10 offset:1536
	v_fma_mix_f32 v12, v6, v110, v180 op_sel_hi:[0,1,0]
	v_fma_mix_f32 v12, v7, v110, v12 op_sel:[0,1,0] op_sel_hi:[0,1,0]
	v_fma_mix_f32 v12, v8, v111, v12 op_sel_hi:[0,1,0]
	v_fma_mix_f32 v12, v9, v111, v12 op_sel:[0,1,0] op_sel_hi:[0,1,0]
	v_fma_mix_f32 v136, v6, v90, v180 op_sel_hi:[0,1,0]
	v_fma_mix_f32 v136, v7, v90, v136 op_sel:[0,1,0] op_sel_hi:[0,1,0]
	v_add_f32_dpp v12, v12, v12 row_ror:1 row_mask:0xf bank_mask:0xf bound_ctrl:1
	v_fma_mix_f32 v136, v8, v91, v136 op_sel_hi:[0,1,0]
	v_fma_mix_f32 v136, v9, v91, v136 op_sel:[0,1,0] op_sel_hi:[0,1,0]
	v_add_f32_dpp v12, v12, v12 row_ror:2 row_mask:0xf bank_mask:0xf bound_ctrl:1
	v_pk_fma_f32 v[48:49], v[118:119], v[72:73], v[6:7] op_sel:[0,1,0]
	v_pk_fma_f32 v[50:51], v[120:121], v[72:73], v[8:9] op_sel:[0,1,0]
	v_add_f32_dpp v12, v12, v12 row_ror:4 row_mask:0xf bank_mask:0xf bound_ctrl:1
	global_store_short v[2:3], v62, off
	v_lshl_add_u64 v[2:3], v[2:3], 0, s[84:85]
	v_add_f32_dpp v12, v12, v12 row_ror:8 row_mask:0xf bank_mask:0xf bound_ctrl:1
	v_pk_fma_f32 v[6:7], v[114:115], v[12:13], v[48:49] op_sel_hi:[1,0,1] neg_lo:[1,0,0] neg_hi:[1,0,0]
	v_pk_fma_f32 v[8:9], v[116:117], v[12:13], v[50:51] op_sel_hi:[1,0,1] neg_lo:[1,0,0] neg_hi:[1,0,0]
	v_pk_mul_f32 v[6:7], v[6:7], v[106:107]
	v_pk_mul_f32 v[8:9], v[8:9], v[108:109]
	v_fma_mix_f32 v137, v6, v112, v180 op_sel_hi:[0,1,0]
	v_fma_mix_f32 v137, v7, v112, v137 op_sel:[0,1,0] op_sel_hi:[0,1,0]
	v_fma_mix_f32 v137, v8, v113, v137 op_sel_hi:[0,1,0]
	v_fma_mix_f32 v137, v9, v113, v137 op_sel:[0,1,0] op_sel_hi:[0,1,0]
	v_add_f32_dpp v130, v130, v130 row_ror:8 row_mask:0xf bank_mask:0xc
	v_add_f32_dpp v130, v122, v122 row_ror:8 row_mask:0xf bank_mask:0x3
	v_add_f32_dpp v131, v131, v131 row_ror:8 row_mask:0xf bank_mask:0xc
	v_add_f32_dpp v131, v123, v123 row_ror:8 row_mask:0xf bank_mask:0x3
	v_add_f32_dpp v132, v132, v132 row_ror:8 row_mask:0xf bank_mask:0xc
	v_add_f32_dpp v132, v124, v124 row_ror:8 row_mask:0xf bank_mask:0x3
	v_add_f32_dpp v133, v133, v133 row_ror:8 row_mask:0xf bank_mask:0xc
	v_add_f32_dpp v133, v125, v125 row_ror:8 row_mask:0xf bank_mask:0x3
	v_add_f32_dpp v134, v134, v134 row_ror:8 row_mask:0xf bank_mask:0xc
	v_add_f32_dpp v134, v126, v126 row_ror:8 row_mask:0xf bank_mask:0x3
	v_add_f32_dpp v135, v135, v135 row_ror:8 row_mask:0xf bank_mask:0xc
	v_add_f32_dpp v135, v127, v127 row_ror:8 row_mask:0xf bank_mask:0x3
	v_add_f32_dpp v136, v136, v136 row_ror:8 row_mask:0xf bank_mask:0xc
	v_add_f32_dpp v136, v128, v128 row_ror:8 row_mask:0xf bank_mask:0x3
	v_add_f32_dpp v137, v137, v137 row_ror:8 row_mask:0xf bank_mask:0xc
	v_add_f32_dpp v137, v129, v129 row_ror:8 row_mask:0xf bank_mask:0x3
	v_add_f32_dpp v134, v134, v134 row_ror:4 row_mask:0xf bank_mask:0xa
	v_add_f32_dpp v134, v130, v130 row_ror:12 row_mask:0xf bank_mask:0x5
	v_add_f32_dpp v135, v135, v135 row_ror:4 row_mask:0xf bank_mask:0xa
	v_add_f32_dpp v135, v131, v131 row_ror:12 row_mask:0xf bank_mask:0x5
	v_add_f32_dpp v136, v136, v136 row_ror:4 row_mask:0xf bank_mask:0xa
	v_add_f32_dpp v136, v132, v132 row_ror:12 row_mask:0xf bank_mask:0x5
	v_add_f32_dpp v137, v137, v137 row_ror:4 row_mask:0xf bank_mask:0xa
	v_add_f32_dpp v137, v133, v133 row_ror:12 row_mask:0xf bank_mask:0x5
	v_cndmask_b32_e64 v62, v136, v134, s[38:39]
	v_cndmask_b32_e64 v63, v134, v136, s[38:39]
	v_cndmask_b32_e64 v64, v137, v135, s[38:39]
	v_cndmask_b32_e64 v65, v135, v137, s[38:39]
	v_add_f32_dpp v62, v63, v62 quad_perm:[2,3,0,1] row_mask:0xf bank_mask:0xf bound_ctrl:1
	s_nop 0
	v_add_f32_dpp v63, v65, v64 quad_perm:[2,3,0,1] row_mask:0xf bank_mask:0xf bound_ctrl:1
	v_cndmask_b32_e64 v65, v63, v62, s[40:41]
	v_cndmask_b32_e64 v62, v62, v63, s[40:41]
	s_nop 1
	v_add_f32_dpp v62, v62, v65 quad_perm:[1,0,3,2] row_mask:0xf bank_mask:0xf bound_ctrl:1
	v_cvt_pk_bf16_f32 v62, v62, v62
	global_store_short v[2:3], v62, off
	s_cmp_lg_u32 s28, 0x800000
	s_cbranch_scc1 .Lscan_cons_chunk
	s_branch .LBB0_53
